# nt cache hints: P5 gate loads (read once), P1 gate stores (re-read much later), P0b x loads
# speedup vs baseline: 1.0362x; 1.0156x over previous
.LBB0_77:
	s_add_i32 s10, s2, s34
	s_cmpk_lt_i32 s10, 0x4000
	s_cselect_b32 s4, s10, s2
	s_ashr_i32 s3, s2, 31
	s_lshl_b64 s[6:7], s[2:3], 13
	v_lshl_add_u64 v[86:87], v[80:81], 0, s[6:7]
	global_load_dwordx4 v[76:79], v[86:87], off nt
	global_load_dwordx4 v[68:71], v[86:87], off offset:1024 nt
	global_load_dwordx4 v[72:75], v[86:87], off offset:2048 nt
	global_load_dwordx4 v[64:67], v[86:87], off offset:3072 nt
	s_ashr_i32 s5, s4, 31
	s_lshl_b64 s[6:7], s[4:5], 13
	v_add_co_u32_e32 v124, vcc, s1, v86
	v_lshl_add_u64 v[128:129], v[80:81], 0, s[6:7]
	s_nop 0
	v_addc_co_u32_e32 v125, vcc, 0, v87, vcc
	v_add_co_u32_e32 v140, vcc, s1, v128
	global_load_dwordx4 v[96:99], v[128:129], off nt
	global_load_dwordx4 v[100:103], v[128:129], off offset:1024 nt
	global_load_dwordx4 v[104:107], v[128:129], off offset:2048 nt
	global_load_dwordx4 v[108:111], v[124:125], off offset:1024 nt
	global_load_dwordx4 v[112:115], v[124:125], off nt
	global_load_dwordx4 v[116:119], v[128:129], off offset:3072 nt
	global_load_dwordx4 v[120:123], v[124:125], off offset:3072 nt
	s_nop 0
	global_load_dwordx4 v[124:127], v[124:125], off offset:2048 nt
	v_addc_co_u32_e32 v141, vcc, 0, v129, vcc
	global_load_dwordx4 v[128:131], v[140:141], off offset:1024 nt
	global_load_dwordx4 v[132:135], v[140:141], off nt
	global_load_dwordx4 v[136:139], v[140:141], off offset:3072 nt
	s_nop 0
	global_load_dwordx4 v[140:143], v[140:141], off offset:2048 nt
	s_lshl_b64 s[8:9], s[2:3], 12
	s_add_i32 s2, s10, s34
	s_lshl_b64 s[4:5], s[4:5], 12
	v_lshl_add_u64 v[84:85], v[82:83], 0, s[8:9]
	s_cmpk_gt_i32 s2, 0x3fff
	v_lshl_add_u64 v[86:87], v[82:83], 0, s[4:5]
	s_waitcnt vmcnt(15)
	v_mov_b32_e32 v146, v77
	s_waitcnt vmcnt(14)
	v_mov_b32_e32 v147, v69
	v_mov_b32_e32 v150, v79
	v_mov_b32_e32 v151, v71
	s_waitcnt vmcnt(13)
	v_pk_mul_f32 v[152:153], v[74:75], v[74:75]
	v_pk_mul_f32 v[154:155], v[72:73], v[72:73]
	v_mov_b32_e32 v144, v76
	v_mov_b32_e32 v145, v68
	v_mov_b32_e32 v148, v78
	v_mov_b32_e32 v149, v70
	v_pk_mul_f32 v[146:147], v[146:147], v[146:147]
	v_pk_mul_f32 v[150:151], v[150:151], v[150:151]
	v_pk_mov_b32 v[162:163], v[154:155], v[152:153] op_sel:[1,0]
	v_mov_b32_e32 v155, v153
	s_waitcnt vmcnt(11)
	v_mov_b32_e32 v170, v97
	s_waitcnt vmcnt(10)
	v_mov_b32_e32 v171, v101
	v_mov_b32_e32 v174, v99
	v_mov_b32_e32 v175, v103
	v_mov_b32_e32 v160, v96
	v_mov_b32_e32 v161, v100
	s_waitcnt vmcnt(9)
	v_pk_mul_f32 v[152:153], v[106:107], v[106:107]
	v_pk_mul_f32 v[164:165], v[104:105], v[104:105]
	v_mov_b32_e32 v172, v98
	v_mov_b32_e32 v173, v102
	v_pk_fma_f32 v[144:145], v[144:145], v[144:145], v[146:147]
	v_pk_fma_f32 v[146:147], v[148:149], v[148:149], v[150:151]
	v_pk_add_f32 v[148:149], v[162:163], v[154:155]
	v_pk_mul_f32 v[154:155], v[170:171], v[170:171]
	v_pk_mul_f32 v[162:163], v[174:175], v[174:175]
	v_mul_f32_e32 v156, v65, v65
	v_mul_f32_e32 v158, v67, v67
	v_pk_mov_b32 v[150:151], v[164:165], v[152:153] op_sel:[1,0]
	v_mov_b32_e32 v165, v153
	v_pk_add_f32 v[144:145], v[144:145], v[146:147]
	v_pk_fma_f32 v[146:147], v[160:161], v[160:161], v[154:155]
	v_pk_fma_f32 v[154:155], v[172:173], v[172:173], v[162:163]
	s_waitcnt vmcnt(7)
	v_mul_f32_e32 v95, v114, v114
	v_pk_fma_f32 v[156:157], v[64:65], v[64:65], v[156:157] op_sel_hi:[1,1,0]
	v_mul_f32_e32 v177, v115, v115
	v_pk_fma_f32 v[158:159], v[66:67], v[66:67], v[158:159] op_sel_hi:[1,1,0]
	s_waitcnt vmcnt(6)
	v_mul_f32_e32 v176, v117, v117
	v_mul_f32_e32 v178, v119, v119
	v_mul_f32_e32 v186, v113, v113
	v_mul_f32_e32 v187, v112, v112
	v_pk_add_f32 v[150:151], v[150:151], v[164:165]
	v_pk_add_f32 v[148:149], v[148:149], v[148:149] op_sel:[0,1] op_sel_hi:[1,0]
	v_pk_add_f32 v[146:147], v[146:147], v[154:155]
	v_pk_add_f32 v[144:145], v[144:145], v[144:145] op_sel:[0,1] op_sel_hi:[1,0]
	v_pk_mul_f32 v[166:167], v[110:111], v[110:111]
	v_pk_mul_f32 v[168:169], v[108:109], v[108:109]
	v_mov_b32_e32 v157, v95
	v_mov_b32_e32 v159, v177
	s_waitcnt vmcnt(2)
	v_mul_f32_e32 v95, v134, v134
	v_pk_fma_f32 v[174:175], v[116:117], v[116:117], v[176:177] op_sel_hi:[1,1,0]
	v_mul_f32_e32 v190, v135, v135
	v_pk_fma_f32 v[176:177], v[118:119], v[118:119], v[178:179] op_sel_hi:[1,1,0]
	v_mul_f32_e32 v195, v133, v133
	v_mul_f32_e32 v196, v132, v132
	v_mov_b32_e32 v149, v186
	v_pk_add_f32 v[150:151], v[150:151], v[150:151] op_sel:[0,1] op_sel_hi:[1,0]
	v_mov_b32_e32 v145, v187
	v_pk_add_f32 v[146:147], v[146:147], v[146:147] op_sel:[0,1] op_sel_hi:[1,0]
	v_pk_mov_b32 v[152:153], v[168:169], v[166:167] op_sel:[1,0]
	v_mov_b32_e32 v169, v167
	v_pk_mul_f32 v[166:167], v[130:131], v[130:131]
	v_pk_mul_f32 v[170:171], v[128:129], v[128:129]
	v_pk_add_f32 v[156:157], v[156:157], v[158:159]
	v_mov_b32_e32 v175, v95
	v_mov_b32_e32 v177, v190
	v_mov_b32_e32 v151, v195
	v_pk_add_f32 v[144:145], v[144:145], v[148:149]
	v_mov_b32_e32 v147, v196
	v_mul_f32_e32 v183, v122, v122
	v_mul_f32_e32 v180, v125, v125
	v_mul_f32_e32 v182, v127, v127
	v_pk_add_f32 v[152:153], v[152:153], v[168:169]
	v_pk_mov_b32 v[158:159], v[170:171], v[166:167] op_sel:[1,0]
	v_mov_b32_e32 v171, v167
	v_pk_add_f32 v[154:155], v[174:175], v[176:177]
	v_pk_add_f32 v[144:145], v[144:145], v[156:157]
	v_pk_add_f32 v[146:147], v[146:147], v[150:151]
	v_mul_f32_e32 v185, v123, v123
	v_mul_f32_e32 v188, v120, v120
	v_mul_f32_e32 v189, v121, v121
	v_pk_fma_f32 v[178:179], v[124:125], v[124:125], v[180:181] op_sel_hi:[1,1,0]
	v_pk_fma_f32 v[180:181], v[126:127], v[126:127], v[182:183] op_sel_hi:[1,1,0]
	s_waitcnt vmcnt(0)
	v_mul_f32_e32 v182, v141, v141
	v_mul_f32_e32 v184, v143, v143
	v_pk_add_f32 v[158:159], v[158:159], v[170:171]
	v_pk_add_f32 v[152:153], v[152:153], v[152:153] op_sel:[0,1] op_sel_hi:[1,0]
	v_pk_add_f32 v[146:147], v[146:147], v[154:155]
	v_pk_add_f32 v[144:145], v[144:145], v[144:145] op_sel:[0,1] op_sel_hi:[1,0]
	v_mul_f32_e32 v191, v138, v138
	v_mul_f32_e32 v194, v139, v139
	v_mul_f32_e32 v197, v136, v136
	v_mul_f32_e32 v198, v137, v137
	v_mov_b32_e32 v179, v183
	v_mov_b32_e32 v181, v185
	v_pk_fma_f32 v[160:161], v[140:141], v[140:141], v[182:183] op_sel_hi:[1,1,0]
	v_pk_fma_f32 v[162:163], v[142:143], v[142:143], v[184:185] op_sel_hi:[1,1,0]
	v_mov_b32_e32 v153, v189
	v_pk_add_f32 v[158:159], v[158:159], v[158:159] op_sel:[0,1] op_sel_hi:[1,0]
	v_mov_b32_e32 v145, v188
	v_pk_add_f32 v[146:147], v[146:147], v[146:147] op_sel:[0,1] op_sel_hi:[1,0]
	v_pk_add_f32 v[164:165], v[178:179], v[180:181]
	v_mov_b32_e32 v161, v191
	v_mov_b32_e32 v163, v194
	v_mov_b32_e32 v159, v198
	v_pk_add_f32 v[144:145], v[144:145], v[152:153]
	v_mov_b32_e32 v147, v197
	v_pk_add_f32 v[160:161], v[160:161], v[162:163]
	v_pk_add_f32 v[144:145], v[144:145], v[164:165]
	v_pk_add_f32 v[146:147], v[146:147], v[158:159]
	v_add_f32_e32 v95, v144, v145
	v_pk_add_f32 v[144:145], v[146:147], v[160:161]
	ds_bpermute_b32 v146, v88, v95
	v_add_f32_e32 v144, v144, v145
	ds_bpermute_b32 v145, v88, v144
	s_waitcnt lgkmcnt(1)
	v_add_f32_e32 v95, v95, v146
	ds_bpermute_b32 v146, v89, v95
	s_waitcnt lgkmcnt(1)
	v_add_f32_e32 v144, v144, v145
	ds_bpermute_b32 v145, v89, v144
	s_waitcnt lgkmcnt(1)
	v_add_f32_e32 v95, v95, v146
	ds_bpermute_b32 v146, v90, v95
	s_waitcnt lgkmcnt(1)
	v_add_f32_e32 v144, v144, v145
	ds_bpermute_b32 v145, v90, v144
	s_waitcnt lgkmcnt(1)
	v_add_f32_e32 v95, v95, v146
	ds_bpermute_b32 v146, v91, v95
	s_waitcnt lgkmcnt(1)
	v_add_f32_e32 v144, v144, v145
	ds_bpermute_b32 v145, v91, v144
	s_waitcnt lgkmcnt(1)
	v_add_f32_e32 v95, v95, v146
	ds_bpermute_b32 v146, v92, v95
	s_waitcnt lgkmcnt(1)
	v_add_f32_e32 v144, v144, v145
	ds_bpermute_b32 v145, v92, v144
	s_waitcnt lgkmcnt(1)
	v_add_f32_e32 v95, v95, v146
	ds_bpermute_b32 v146, v93, v95
	s_waitcnt lgkmcnt(1)
	v_add_f32_e32 v144, v144, v145
	ds_bpermute_b32 v145, v93, v144
	s_waitcnt lgkmcnt(1)
	v_add_f32_e32 v95, v95, v146
	v_fmamk_f32 v95, v95, 0x3a000000, v94
	s_waitcnt lgkmcnt(0)
	v_add_f32_e32 v145, v144, v145
	v_rsq_f32_e32 v144, v95
	v_fmamk_f32 v95, v145, 0x3a000000, v94
	v_rsq_f32_e32 v146, v95
	v_pk_mul_f32 v[76:77], v[144:145], v[76:77] op_sel_hi:[0,1]
	v_pk_mul_f32 v[78:79], v[144:145], v[78:79] op_sel_hi:[0,1]
	v_pk_mul_f32 v[68:69], v[144:145], v[68:69] op_sel_hi:[0,1]
	v_pk_mul_f32 v[70:71], v[144:145], v[70:71] op_sel_hi:[0,1]
	v_pk_mul_f32 v[72:73], v[144:145], v[72:73] op_sel_hi:[0,1]
	v_pk_mul_f32 v[74:75], v[144:145], v[74:75] op_sel_hi:[0,1]
	v_pk_mul_f32 v[64:65], v[144:145], v[64:65] op_sel_hi:[0,1]
	v_pk_mul_f32 v[66:67], v[144:145], v[66:67] op_sel_hi:[0,1]
	v_pk_mul_f32 v[112:113], v[144:145], v[112:113] op_sel_hi:[0,1]
	v_pk_mul_f32 v[114:115], v[144:145], v[114:115] op_sel_hi:[0,1]
	v_pk_mul_f32 v[108:109], v[144:145], v[108:109] op_sel_hi:[0,1]
	v_pk_mul_f32 v[110:111], v[144:145], v[110:111] op_sel_hi:[0,1]
	v_pk_mul_f32 v[124:125], v[144:145], v[124:125] op_sel_hi:[0,1]
	v_pk_mul_f32 v[126:127], v[144:145], v[126:127] op_sel_hi:[0,1]
	v_pk_mul_f32 v[120:121], v[144:145], v[120:121] op_sel_hi:[0,1]
	v_pk_mul_f32 v[122:123], v[144:145], v[122:123] op_sel_hi:[0,1]
	v_pk_fma_f32 v[78:79], v[2:3], v[78:79], v[10:11]
	v_pk_fma_f32 v[76:77], v[0:1], v[76:77], v[8:9]
	v_pk_mul_f32 v[96:97], v[146:147], v[96:97] op_sel_hi:[0,1]
	v_pk_mul_f32 v[98:99], v[146:147], v[98:99] op_sel_hi:[0,1]
	v_pk_fma_f32 v[70:71], v[6:7], v[70:71], v[14:15]
	v_pk_fma_f32 v[68:69], v[4:5], v[68:69], v[12:13]
	v_pk_mul_f32 v[100:101], v[146:147], v[100:101] op_sel_hi:[0,1]
	v_pk_mul_f32 v[102:103], v[146:147], v[102:103] op_sel_hi:[0,1]
	v_pk_fma_f32 v[74:75], v[18:19], v[74:75], v[26:27]
	v_pk_fma_f32 v[72:73], v[16:17], v[72:73], v[24:25]
	v_pk_mul_f32 v[104:105], v[146:147], v[104:105] op_sel_hi:[0,1]
	v_pk_mul_f32 v[106:107], v[146:147], v[106:107] op_sel_hi:[0,1]
	v_pk_fma_f32 v[66:67], v[22:23], v[66:67], v[30:31]
	v_pk_fma_f32 v[64:65], v[20:21], v[64:65], v[28:29]
	v_pk_mul_f32 v[116:117], v[146:147], v[116:117] op_sel_hi:[0,1]
	v_pk_mul_f32 v[118:119], v[146:147], v[118:119] op_sel_hi:[0,1]
	v_pk_fma_f32 v[114:115], v[34:35], v[114:115], v[42:43]
	v_pk_fma_f32 v[112:113], v[32:33], v[112:113], v[40:41]
	v_pk_mul_f32 v[132:133], v[146:147], v[132:133] op_sel_hi:[0,1]
	v_pk_mul_f32 v[134:135], v[146:147], v[134:135] op_sel_hi:[0,1]
	v_pk_fma_f32 v[110:111], v[38:39], v[110:111], v[46:47]
	v_pk_fma_f32 v[108:109], v[36:37], v[108:109], v[44:45]
	v_pk_mul_f32 v[128:129], v[146:147], v[128:129] op_sel_hi:[0,1]
	v_pk_mul_f32 v[130:131], v[146:147], v[130:131] op_sel_hi:[0,1]
	v_pk_fma_f32 v[126:127], v[50:51], v[126:127], v[58:59]
	v_pk_fma_f32 v[124:125], v[48:49], v[124:125], v[56:57]
	v_pk_mul_f32 v[140:141], v[146:147], v[140:141] op_sel_hi:[0,1]
	v_pk_mul_f32 v[142:143], v[146:147], v[142:143] op_sel_hi:[0,1]
	v_pk_fma_f32 v[122:123], v[54:55], v[122:123], v[62:63]
	v_pk_fma_f32 v[120:121], v[52:53], v[120:121], v[60:61]
	v_pk_mul_f32 v[136:137], v[146:147], v[136:137] op_sel_hi:[0,1]
	v_pk_mul_f32 v[138:139], v[146:147], v[138:139] op_sel_hi:[0,1]
	v_pk_fma_f32 v[98:99], v[2:3], v[98:99], v[10:11]
	v_pk_fma_f32 v[96:97], v[0:1], v[96:97], v[8:9]
	v_cvt_pk_bf16_f32 v76, v76, v77
	v_cvt_pk_bf16_f32 v77, v78, v79
	v_pk_fma_f32 v[78:79], v[6:7], v[102:103], v[14:15]
	v_pk_fma_f32 v[100:101], v[4:5], v[100:101], v[12:13]
	v_cvt_pk_bf16_f32 v68, v68, v69
	v_cvt_pk_bf16_f32 v69, v70, v71
	v_pk_fma_f32 v[70:71], v[18:19], v[106:107], v[26:27]
	v_pk_fma_f32 v[102:103], v[16:17], v[104:105], v[24:25]
	v_cvt_pk_bf16_f32 v72, v72, v73
	v_cvt_pk_bf16_f32 v73, v74, v75
	v_pk_fma_f32 v[74:75], v[22:23], v[118:119], v[30:31]
	v_pk_fma_f32 v[104:105], v[20:21], v[116:117], v[28:29]
	v_cvt_pk_bf16_f32 v64, v64, v65
	v_cvt_pk_bf16_f32 v65, v66, v67
	v_pk_fma_f32 v[66:67], v[34:35], v[134:135], v[42:43]
	v_pk_fma_f32 v[106:107], v[32:33], v[132:133], v[40:41]
	v_cvt_pk_bf16_f32 v112, v112, v113
	v_cvt_pk_bf16_f32 v113, v114, v115
	v_pk_fma_f32 v[114:115], v[38:39], v[130:131], v[46:47]
	v_pk_fma_f32 v[116:117], v[36:37], v[128:129], v[44:45]
	v_cvt_pk_bf16_f32 v108, v108, v109
	v_cvt_pk_bf16_f32 v109, v110, v111
	v_pk_fma_f32 v[110:111], v[50:51], v[142:143], v[58:59]
	v_pk_fma_f32 v[118:119], v[48:49], v[140:141], v[56:57]
	v_cvt_pk_bf16_f32 v124, v124, v125
	v_cvt_pk_bf16_f32 v125, v126, v127
	v_pk_fma_f32 v[126:127], v[54:55], v[138:139], v[62:63]
	v_pk_fma_f32 v[128:129], v[52:53], v[136:137], v[60:61]
	v_cvt_pk_bf16_f32 v120, v120, v121
	v_cvt_pk_bf16_f32 v121, v122, v123
	v_cvt_pk_bf16_f32 v96, v96, v97
	v_cvt_pk_bf16_f32 v97, v98, v99
	global_store_dwordx2 v[84:85], v[76:77], off
	v_cvt_pk_bf16_f32 v76, v100, v101
	v_cvt_pk_bf16_f32 v77, v78, v79
	global_store_dwordx2 v[84:85], v[68:69], off offset:512
	v_cvt_pk_bf16_f32 v68, v102, v103
	v_cvt_pk_bf16_f32 v69, v70, v71
	global_store_dwordx2 v[84:85], v[72:73], off offset:1024
	v_cvt_pk_bf16_f32 v70, v104, v105
	v_cvt_pk_bf16_f32 v71, v74, v75
	global_store_dwordx2 v[84:85], v[64:65], off offset:1536
	v_cvt_pk_bf16_f32 v64, v106, v107
	v_cvt_pk_bf16_f32 v65, v66, v67
	global_store_dwordx2 v[84:85], v[112:113], off offset:2048
	v_cvt_pk_bf16_f32 v66, v116, v117
	v_cvt_pk_bf16_f32 v67, v114, v115
	global_store_dwordx2 v[84:85], v[108:109], off offset:2560
	v_cvt_pk_bf16_f32 v72, v118, v119
	v_cvt_pk_bf16_f32 v73, v110, v111
	global_store_dwordx2 v[84:85], v[124:125], off offset:3072
	v_cvt_pk_bf16_f32 v74, v128, v129
	v_cvt_pk_bf16_f32 v75, v126, v127
	global_store_dwordx2 v[84:85], v[120:121], off offset:3584
	global_store_dwordx2 v[86:87], v[96:97], off
	global_store_dwordx2 v[86:87], v[76:77], off offset:512
	global_store_dwordx2 v[86:87], v[68:69], off offset:1024
	global_store_dwordx2 v[86:87], v[70:71], off offset:1536
	global_store_dwordx2 v[86:87], v[64:65], off offset:2048
	global_store_dwordx2 v[86:87], v[66:67], off offset:2560
	global_store_dwordx2 v[86:87], v[72:73], off offset:3072
	global_store_dwordx2 v[86:87], v[74:75], off offset:3584
	s_cbranch_scc0 .LBB0_77

.LBB0_189:
	s_andn2_b64 vcc, exec, s[56:57]
	s_cbranch_vccnz .LBB0_191
	s_lshl_b32 s6, s48, 7
	s_addk_i32 s6, 0xf800
	v_lshl_or_b32 v128, v176, 3, s6
	v_or_b32_e32 v148, s77, v128
	v_readlane_b32 s52, v254, 18
	v_lshlrev_b64 v[128:129], 2, v[148:149]
	v_readlane_b32 s62, v254, 28
	v_readlane_b32 s63, v254, 29
	v_lshl_add_u64 v[140:141], s[20:21], 0, v[128:129]
	v_lshl_add_u64 v[160:161], v[148:149], 1, s[2:3]
	v_lshl_add_u64 v[132:133], s[62:63], 0, v[128:129]
	global_load_dwordx4 v[128:131], v[132:133], off offset:16
	global_load_dwordx4 v[136:139], v[132:133], off
	s_nop 0
	global_load_dwordx4 v[132:135], v[140:141], off offset:16
	s_nop 0
	global_load_dwordx4 v[140:143], v[140:141], off
	v_ashrrev_i32_e32 v157, 31, v156
	v_lshlrev_b64 v[158:159], 13, v[156:157]
	v_lshl_add_u64 v[158:159], v[160:161], 0, v[158:159]
	v_readlane_b32 s53, v254, 19
	v_readlane_b32 s54, v254, 20
	v_readlane_b32 s55, v254, 21
	v_readlane_b32 s56, v254, 22
	v_readlane_b32 s57, v254, 23
	v_readlane_b32 s58, v254, 24
	v_readlane_b32 s59, v254, 25
	v_readlane_b32 s60, v254, 26
	v_readlane_b32 s61, v254, 27
	v_readlane_b32 s64, v254, 30
	v_readlane_b32 s65, v254, 31
	v_readlane_b32 s66, v254, 32
	v_readlane_b32 s67, v254, 33
	s_waitcnt vmcnt(0)
	v_add_f32_e32 v148, v124, v136
	v_mul_f32_e32 v148, 0xbfb8aa3b, v148
	v_exp_f32_e32 v148, v148
	v_add_f32_e32 v157, v116, v140
	v_mul_f32_e32 v157, 0xbfb8aa3b, v157
	v_exp_f32_e32 v162, v157
	v_add_f32_e32 v148, 1.0, v148
	v_rcp_f32_e32 v164, v148
	v_add_f32_e32 v148, v125, v137
	v_mul_f32_e32 v148, 0xbfb8aa3b, v148
	v_exp_f32_e32 v148, v148
	v_add_f32_e32 v157, v117, v141
	v_mul_f32_e32 v157, 0xbfb8aa3b, v157
	v_exp_f32_e32 v163, v157
	v_add_f32_e32 v148, 1.0, v148
	v_rcp_f32_e32 v165, v148
	v_pk_add_f32 v[162:163], v[162:163], 1.0 op_sel_hi:[1,0]
	s_nop 0
	v_rcp_f32_e32 v148, v162
	v_rcp_f32_e32 v157, v163
	v_pk_mul_f32 v[162:163], v[164:165], v[162:163]
	v_add_f32_e32 v164, v126, v138
	v_mul_f32_e32 v164, 0xbfb8aa3b, v164
	v_exp_f32_e32 v165, v164
	v_add_f32_e32 v164, v118, v142
	v_mul_f32_e32 v164, 0xbfb8aa3b, v164
	v_exp_f32_e32 v164, v164
	v_add_f32_e32 v165, 1.0, v165
	v_rcp_f32_e32 v166, v165
	v_add_f32_e32 v165, v127, v139
	v_mul_f32_e32 v165, 0xbfb8aa3b, v165
	v_exp_f32_e32 v167, v165
	v_add_f32_e32 v165, v119, v143
	v_mul_f32_e32 v165, 0xbfb8aa3b, v165
	v_exp_f32_e32 v165, v165
	v_add_f32_e32 v167, 1.0, v167
	v_rcp_f32_e32 v167, v167
	v_cvt_pk_bf16_f32 v162, v162, v163
	v_pk_add_f32 v[164:165], v[164:165], 1.0 op_sel_hi:[1,0]
	s_nop 0
	v_rcp_f32_e32 v176, v164
	v_rcp_f32_e32 v177, v165
	v_pk_mul_f32 v[164:165], v[166:167], v[164:165]
	v_add_f32_e32 v166, v120, v128
	v_mul_f32_e32 v166, 0xbfb8aa3b, v166
	v_exp_f32_e32 v167, v166
	v_add_f32_e32 v166, v112, v132
	v_mul_f32_e32 v166, 0xbfb8aa3b, v166
	v_exp_f32_e32 v166, v166
	v_add_f32_e32 v167, 1.0, v167
	v_rcp_f32_e32 v168, v167
	v_add_f32_e32 v167, v121, v129
	v_mul_f32_e32 v167, 0xbfb8aa3b, v167
	v_exp_f32_e32 v169, v167
	v_add_f32_e32 v167, v113, v133
	v_mul_f32_e32 v167, 0xbfb8aa3b, v167
	v_exp_f32_e32 v167, v167
	v_add_f32_e32 v169, 1.0, v169
	v_rcp_f32_e32 v169, v169
	v_cvt_pk_bf16_f32 v163, v164, v165
	v_pk_add_f32 v[166:167], v[166:167], 1.0 op_sel_hi:[1,0]
	s_nop 0
	v_rcp_f32_e32 v178, v166
	v_rcp_f32_e32 v179, v167
	v_pk_mul_f32 v[166:167], v[168:169], v[166:167]
	v_add_f32_e32 v168, v122, v130
	v_mul_f32_e32 v168, 0xbfb8aa3b, v168
	v_exp_f32_e32 v169, v168
	v_add_f32_e32 v168, v114, v134
	v_mul_f32_e32 v168, 0xbfb8aa3b, v168
	v_exp_f32_e32 v168, v168
	v_add_f32_e32 v169, 1.0, v169
	v_rcp_f32_e32 v182, v169
	v_add_f32_e32 v169, v123, v131
	v_mul_f32_e32 v169, 0xbfb8aa3b, v169
	v_exp_f32_e32 v180, v169
	v_add_f32_e32 v169, v115, v135
	v_mul_f32_e32 v169, 0xbfb8aa3b, v169
	v_exp_f32_e32 v169, v169
	v_add_f32_e32 v180, 1.0, v180
	v_rcp_f32_e32 v183, v180
	v_cvt_pk_bf16_f32 v164, v166, v167
	v_pk_add_f32 v[184:185], v[168:169], 1.0 op_sel_hi:[1,0]
	v_add_co_u32_e32 v166, vcc, s91, v158
	v_pk_mul_f32 v[168:169], v[182:183], v[184:185]
	v_rcp_f32_e32 v180, v184
	v_cvt_pk_bf16_f32 v165, v168, v169
	flat_store_dwordx4 v[158:159], v[162:165] nt
	v_rcp_f32_e32 v181, v185
	v_addc_co_u32_e32 v167, vcc, 0, v159, vcc
	v_cvt_pk_bf16_f32 v162, v148, v157
	v_add_f32_e32 v148, v108, v136
	v_mul_f32_e32 v148, 0xbfb8aa3b, v148
	v_exp_f32_e32 v148, v148
	v_cvt_pk_bf16_f32 v163, v176, v177
	v_cvt_pk_bf16_f32 v164, v178, v179
	v_cvt_pk_bf16_f32 v165, v180, v181
	v_add_f32_e32 v148, 1.0, v148
	flat_store_dwordx4 v[166:167], v[162:165] nt
	v_rcp_f32_e32 v166, v148
	v_add_f32_e32 v148, v109, v137
	v_mul_f32_e32 v148, 0xbfb8aa3b, v148
	v_add_f32_e32 v157, v104, v140
	v_exp_f32_e32 v148, v148
	v_mul_f32_e32 v157, 0xbfb8aa3b, v157
	v_exp_f32_e32 v164, v157
	v_add_f32_e32 v157, v105, v141
	v_mul_f32_e32 v157, 0xbfb8aa3b, v157
	v_exp_f32_e32 v165, v157
	v_add_f32_e32 v148, 1.0, v148
	v_rcp_f32_e32 v167, v148
	v_or_b32_e32 v162, 16, v156
	v_pk_add_f32 v[164:165], v[164:165], 1.0 op_sel_hi:[1,0]
	v_ashrrev_i32_e32 v163, 31, v162
	v_rcp_f32_e32 v148, v164
	v_pk_mul_f32 v[166:167], v[166:167], v[164:165]
	v_add_f32_e32 v164, v110, v138
	v_mul_f32_e32 v164, 0xbfb8aa3b, v164
	v_rcp_f32_e32 v157, v165
	v_exp_f32_e32 v165, v164
	v_add_f32_e32 v164, v106, v142
	v_mul_f32_e32 v164, 0xbfb8aa3b, v164
	v_exp_f32_e32 v164, v164
	v_add_f32_e32 v165, 1.0, v165
	v_rcp_f32_e32 v168, v165
	v_add_f32_e32 v165, v111, v139
	v_mul_f32_e32 v165, 0xbfb8aa3b, v165
	v_exp_f32_e32 v169, v165
	v_add_f32_e32 v165, v107, v143
	v_mul_f32_e32 v165, 0xbfb8aa3b, v165
	v_exp_f32_e32 v165, v165
	v_add_f32_e32 v169, 1.0, v169
	v_rcp_f32_e32 v169, v169
	v_lshlrev_b64 v[162:163], 13, v[162:163]
	v_pk_add_f32 v[164:165], v[164:165], 1.0 op_sel_hi:[1,0]
	v_lshl_add_u64 v[180:181], v[160:161], 0, v[162:163]
	v_rcp_f32_e32 v182, v164
	v_pk_mul_f32 v[168:169], v[168:169], v[164:165]
	v_add_f32_e32 v164, v100, v128
	v_mul_f32_e32 v164, 0xbfb8aa3b, v164
	v_rcp_f32_e32 v183, v165
	v_exp_f32_e32 v165, v164
	v_add_f32_e32 v164, v96, v132
	v_mul_f32_e32 v164, 0xbfb8aa3b, v164
	v_exp_f32_e32 v164, v164
	v_add_f32_e32 v165, 1.0, v165
	v_rcp_f32_e32 v176, v165
	v_add_f32_e32 v165, v101, v129
	v_mul_f32_e32 v165, 0xbfb8aa3b, v165
	v_exp_f32_e32 v177, v165
	v_add_f32_e32 v165, v97, v133
	v_mul_f32_e32 v165, 0xbfb8aa3b, v165
	v_exp_f32_e32 v165, v165
	v_add_f32_e32 v177, 1.0, v177
	v_rcp_f32_e32 v177, v177
	v_cvt_pk_bf16_f32 v162, v166, v167
	v_pk_add_f32 v[164:165], v[164:165], 1.0 op_sel_hi:[1,0]
	v_cvt_pk_bf16_f32 v163, v168, v169
	v_rcp_f32_e32 v184, v164
	v_pk_mul_f32 v[176:177], v[176:177], v[164:165]
	v_add_f32_e32 v164, v102, v130
	v_mul_f32_e32 v164, 0xbfb8aa3b, v164
	v_rcp_f32_e32 v185, v165
	v_exp_f32_e32 v165, v164
	v_add_f32_e32 v164, v98, v134
	v_mul_f32_e32 v164, 0xbfb8aa3b, v164
	v_exp_f32_e32 v164, v164
	v_add_f32_e32 v165, 1.0, v165
	v_rcp_f32_e32 v178, v165
	v_add_f32_e32 v165, v103, v131
	v_mul_f32_e32 v165, 0xbfb8aa3b, v165
	v_exp_f32_e32 v179, v165
	v_add_f32_e32 v165, v99, v135
	v_mul_f32_e32 v165, 0xbfb8aa3b, v165
	v_exp_f32_e32 v165, v165
	v_add_f32_e32 v179, 1.0, v179
	v_rcp_f32_e32 v179, v179
	v_add_co_u32_e32 v166, vcc, s91, v180
	v_pk_add_f32 v[164:165], v[164:165], 1.0 op_sel_hi:[1,0]
	s_nop 0
	v_addc_co_u32_e32 v167, vcc, 0, v181, vcc
	v_pk_mul_f32 v[178:179], v[178:179], v[164:165]
	v_rcp_f32_e32 v186, v164
	v_rcp_f32_e32 v187, v165
	v_cvt_pk_bf16_f32 v164, v176, v177
	v_cvt_pk_bf16_f32 v165, v178, v179
	flat_store_dwordx4 v[180:181], v[162:165] nt
	s_nop 1
	v_cvt_pk_bf16_f32 v162, v148, v157
	v_add_f32_e32 v148, v92, v136
	v_mul_f32_e32 v148, 0xbfb8aa3b, v148
	v_exp_f32_e32 v148, v148
	v_cvt_pk_bf16_f32 v163, v182, v183
	v_cvt_pk_bf16_f32 v164, v184, v185
	v_cvt_pk_bf16_f32 v165, v186, v187
	v_add_f32_e32 v148, 1.0, v148
	flat_store_dwordx4 v[166:167], v[162:165] nt
	v_rcp_f32_e32 v166, v148
	v_add_f32_e32 v148, v93, v137
	v_mul_f32_e32 v148, 0xbfb8aa3b, v148
	v_add_f32_e32 v157, v88, v140
	v_exp_f32_e32 v148, v148
	v_mul_f32_e32 v157, 0xbfb8aa3b, v157
	v_exp_f32_e32 v164, v157
	v_add_f32_e32 v157, v89, v141
	v_mul_f32_e32 v157, 0xbfb8aa3b, v157
	v_exp_f32_e32 v165, v157
	v_add_f32_e32 v148, 1.0, v148
	v_rcp_f32_e32 v167, v148
	v_or_b32_e32 v162, 32, v156
	v_pk_add_f32 v[164:165], v[164:165], 1.0 op_sel_hi:[1,0]
	v_ashrrev_i32_e32 v163, 31, v162
	v_rcp_f32_e32 v148, v164
	v_pk_mul_f32 v[166:167], v[166:167], v[164:165]
	v_add_f32_e32 v164, v94, v138
	v_mul_f32_e32 v164, 0xbfb8aa3b, v164
	v_rcp_f32_e32 v157, v165
	v_exp_f32_e32 v165, v164
	v_add_f32_e32 v164, v90, v142
	v_mul_f32_e32 v164, 0xbfb8aa3b, v164
	v_exp_f32_e32 v164, v164
	v_add_f32_e32 v165, 1.0, v165
	v_rcp_f32_e32 v168, v165
	v_add_f32_e32 v165, v95, v139
	v_mul_f32_e32 v165, 0xbfb8aa3b, v165
	v_exp_f32_e32 v169, v165
	v_add_f32_e32 v165, v91, v143
	v_mul_f32_e32 v165, 0xbfb8aa3b, v165
	v_exp_f32_e32 v165, v165
	v_add_f32_e32 v169, 1.0, v169
	v_rcp_f32_e32 v169, v169
	v_lshlrev_b64 v[162:163], 13, v[162:163]
	v_pk_add_f32 v[164:165], v[164:165], 1.0 op_sel_hi:[1,0]
	v_lshl_add_u64 v[180:181], v[160:161], 0, v[162:163]
	v_rcp_f32_e32 v182, v164
	v_pk_mul_f32 v[168:169], v[168:169], v[164:165]
	v_add_f32_e32 v164, v84, v128
	v_mul_f32_e32 v164, 0xbfb8aa3b, v164
	v_rcp_f32_e32 v183, v165
	v_exp_f32_e32 v165, v164
	v_add_f32_e32 v164, v80, v132
	v_mul_f32_e32 v164, 0xbfb8aa3b, v164
	v_exp_f32_e32 v164, v164
	v_add_f32_e32 v165, 1.0, v165
	v_rcp_f32_e32 v176, v165
	v_add_f32_e32 v165, v85, v129
	v_mul_f32_e32 v165, 0xbfb8aa3b, v165
	v_exp_f32_e32 v177, v165
	v_add_f32_e32 v165, v81, v133
	v_mul_f32_e32 v165, 0xbfb8aa3b, v165
	v_exp_f32_e32 v165, v165
	v_add_f32_e32 v177, 1.0, v177
	v_rcp_f32_e32 v177, v177
	v_cvt_pk_bf16_f32 v162, v166, v167
	v_pk_add_f32 v[164:165], v[164:165], 1.0 op_sel_hi:[1,0]
	v_cvt_pk_bf16_f32 v163, v168, v169
	v_rcp_f32_e32 v184, v164
	v_pk_mul_f32 v[176:177], v[176:177], v[164:165]
	v_add_f32_e32 v164, v86, v130
	v_mul_f32_e32 v164, 0xbfb8aa3b, v164
	v_rcp_f32_e32 v185, v165
	v_exp_f32_e32 v165, v164
	v_add_f32_e32 v164, v82, v134
	v_mul_f32_e32 v164, 0xbfb8aa3b, v164
	v_exp_f32_e32 v164, v164
	v_add_f32_e32 v165, 1.0, v165
	v_rcp_f32_e32 v178, v165
	v_add_f32_e32 v165, v87, v131
	v_mul_f32_e32 v165, 0xbfb8aa3b, v165
	v_exp_f32_e32 v179, v165
	v_add_f32_e32 v165, v83, v135
	v_mul_f32_e32 v165, 0xbfb8aa3b, v165
	v_exp_f32_e32 v165, v165
	v_add_f32_e32 v179, 1.0, v179
	v_rcp_f32_e32 v179, v179
	v_add_co_u32_e32 v166, vcc, s91, v180
	v_pk_add_f32 v[164:165], v[164:165], 1.0 op_sel_hi:[1,0]
	s_nop 0
	v_addc_co_u32_e32 v167, vcc, 0, v181, vcc
	v_pk_mul_f32 v[178:179], v[178:179], v[164:165]
	v_rcp_f32_e32 v186, v164
	v_rcp_f32_e32 v187, v165
	v_cvt_pk_bf16_f32 v164, v176, v177
	v_cvt_pk_bf16_f32 v165, v178, v179
	flat_store_dwordx4 v[180:181], v[162:165] nt
	v_or_b32_e32 v156, 48, v156
	s_nop 0
	v_cvt_pk_bf16_f32 v162, v148, v157
	v_add_f32_e32 v148, v76, v136
	v_mul_f32_e32 v148, 0xbfb8aa3b, v148
	v_exp_f32_e32 v148, v148
	v_cvt_pk_bf16_f32 v163, v182, v183
	v_cvt_pk_bf16_f32 v164, v184, v185
	v_cvt_pk_bf16_f32 v165, v186, v187
	v_add_f32_e32 v148, 1.0, v148
	flat_store_dwordx4 v[166:167], v[162:165] nt
	v_ashrrev_i32_e32 v157, 31, v156
	v_lshlrev_b64 v[156:157], 13, v[156:157]
	v_rcp_f32_e32 v164, v148
	v_add_f32_e32 v148, v77, v137
	v_mul_f32_e32 v148, 0xbfb8aa3b, v148
	v_exp_f32_e32 v148, v148
	v_add_f32_e32 v162, v72, v140
	v_add_f32_e32 v163, v73, v141
	v_mul_f32_e32 v162, 0xbfb8aa3b, v162
	v_mul_f32_e32 v163, 0xbfb8aa3b, v163
	v_exp_f32_e32 v162, v162
	v_exp_f32_e32 v163, v163
	v_add_f32_e32 v148, 1.0, v148
	v_rcp_f32_e32 v165, v148
	v_lshl_add_u64 v[156:157], v[160:161], 0, v[156:157]
	v_pk_add_f32 v[162:163], v[162:163], 1.0 op_sel_hi:[1,0]
	s_nop 0
	v_rcp_f32_e32 v148, v162
	v_pk_mul_f32 v[164:165], v[164:165], v[162:163]
	v_add_f32_e32 v162, v78, v138
	v_mul_f32_e32 v162, 0xbfb8aa3b, v162
	v_rcp_f32_e32 v178, v163
	v_exp_f32_e32 v163, v162
	v_add_f32_e32 v162, v74, v142
	v_mul_f32_e32 v162, 0xbfb8aa3b, v162
	v_exp_f32_e32 v162, v162
	v_add_f32_e32 v163, 1.0, v163
	v_rcp_f32_e32 v166, v163
	v_add_f32_e32 v163, v79, v139
	v_mul_f32_e32 v163, 0xbfb8aa3b, v163
	v_exp_f32_e32 v167, v163
	v_add_f32_e32 v163, v75, v143
	v_mul_f32_e32 v163, 0xbfb8aa3b, v163
	v_exp_f32_e32 v163, v163
	v_add_f32_e32 v167, 1.0, v167
	v_rcp_f32_e32 v167, v167
	v_cvt_pk_bf16_f32 v160, v164, v165
	v_pk_add_f32 v[162:163], v[162:163], 1.0 op_sel_hi:[1,0]
	s_nop 0
	v_rcp_f32_e32 v179, v162
	v_pk_mul_f32 v[166:167], v[166:167], v[162:163]
	v_add_f32_e32 v162, v68, v128
	v_mul_f32_e32 v162, 0xbfb8aa3b, v162
	v_rcp_f32_e32 v180, v163
	v_exp_f32_e32 v163, v162
	v_add_f32_e32 v162, v64, v132
	v_mul_f32_e32 v162, 0xbfb8aa3b, v162
	v_exp_f32_e32 v162, v162
	v_add_f32_e32 v163, 1.0, v163
	v_rcp_f32_e32 v168, v163
	v_add_f32_e32 v163, v69, v129
	v_mul_f32_e32 v163, 0xbfb8aa3b, v163
	v_exp_f32_e32 v169, v163
	v_add_f32_e32 v163, v65, v133
	v_mul_f32_e32 v163, 0xbfb8aa3b, v163
	v_exp_f32_e32 v163, v163
	v_add_f32_e32 v169, 1.0, v169
	v_rcp_f32_e32 v169, v169
	v_cvt_pk_bf16_f32 v161, v166, v167
	v_pk_add_f32 v[162:163], v[162:163], 1.0 op_sel_hi:[1,0]
	s_nop 0
	v_rcp_f32_e32 v181, v162
	v_pk_mul_f32 v[168:169], v[168:169], v[162:163]
	v_add_f32_e32 v162, v70, v130
	v_mul_f32_e32 v162, 0xbfb8aa3b, v162
	v_rcp_f32_e32 v182, v163
	v_exp_f32_e32 v163, v162
	v_add_f32_e32 v162, v66, v134
	v_mul_f32_e32 v162, 0xbfb8aa3b, v162
	v_exp_f32_e32 v162, v162
	v_add_f32_e32 v163, 1.0, v163
	v_rcp_f32_e32 v176, v163
	v_add_f32_e32 v163, v71, v131
	v_mul_f32_e32 v163, 0xbfb8aa3b, v163
	v_exp_f32_e32 v177, v163
	v_add_f32_e32 v163, v67, v135
	v_mul_f32_e32 v163, 0xbfb8aa3b, v163
	v_exp_f32_e32 v163, v163
	v_add_f32_e32 v177, 1.0, v177
	v_rcp_f32_e32 v177, v177
	v_pk_add_f32 v[162:163], v[162:163], 1.0 op_sel_hi:[1,0]
	s_nop 0
	v_rcp_f32_e32 v183, v162
	v_pk_mul_f32 v[176:177], v[176:177], v[162:163]
	v_rcp_f32_e32 v184, v163
	v_cvt_pk_bf16_f32 v162, v168, v169
	v_cvt_pk_bf16_f32 v163, v176, v177
	flat_store_dwordx4 v[156:157], v[160:163] nt
	v_add_co_u32_e32 v156, vcc, s91, v156
	s_nop 0
	v_cvt_pk_bf16_f32 v160, v148, v178
	v_add_f32_e32 v148, v60, v136
	v_mul_f32_e32 v148, 0xbfb8aa3b, v148
	v_exp_f32_e32 v148, v148
	v_cvt_pk_bf16_f32 v161, v179, v180
	v_cvt_pk_bf16_f32 v162, v181, v182
	v_cvt_pk_bf16_f32 v163, v183, v184
	v_addc_co_u32_e32 v157, vcc, 0, v157, vcc
	v_add_f32_e32 v148, 1.0, v148
	flat_store_dwordx4 v[156:157], v[160:163] nt
	v_add_f32_e32 v156, v56, v140
	v_add_f32_e32 v157, v57, v141
	v_rcp_f32_e32 v160, v148
	v_add_f32_e32 v148, v61, v137
	v_mul_f32_e32 v148, 0xbfb8aa3b, v148
	v_exp_f32_e32 v148, v148
	v_mul_f32_e32 v156, 0xbfb8aa3b, v156
	v_mul_f32_e32 v157, 0xbfb8aa3b, v157
	v_exp_f32_e32 v156, v156
	v_exp_f32_e32 v157, v157
	v_add_f32_e32 v148, 1.0, v148
	v_rcp_f32_e32 v161, v148
	v_pk_add_f32 v[156:157], v[156:157], 1.0 op_sel_hi:[1,0]
	s_nop 0
	v_rcp_f32_e32 v148, v156
	v_pk_mul_f32 v[160:161], v[160:161], v[156:157]
	v_add_f32_e32 v156, v62, v138
	v_mul_f32_e32 v156, 0xbfb8aa3b, v156
	v_rcp_f32_e32 v168, v157
	v_exp_f32_e32 v157, v156
	v_add_f32_e32 v156, v58, v142
	v_mul_f32_e32 v156, 0xbfb8aa3b, v156
	v_exp_f32_e32 v156, v156
	v_add_f32_e32 v157, 1.0, v157
	v_rcp_f32_e32 v162, v157
	v_add_f32_e32 v157, v63, v139
	v_mul_f32_e32 v157, 0xbfb8aa3b, v157
	v_exp_f32_e32 v163, v157
	v_add_f32_e32 v157, v59, v143
	v_mul_f32_e32 v157, 0xbfb8aa3b, v157
	v_exp_f32_e32 v157, v157
	v_add_f32_e32 v163, 1.0, v163
	v_rcp_f32_e32 v163, v163
	v_cvt_pk_bf16_f32 v160, v160, v161
	v_pk_add_f32 v[156:157], v[156:157], 1.0 op_sel_hi:[1,0]
	s_nop 0
	v_rcp_f32_e32 v169, v156
	v_pk_mul_f32 v[162:163], v[162:163], v[156:157]
	v_add_f32_e32 v156, v52, v128
	v_mul_f32_e32 v156, 0xbfb8aa3b, v156
	v_rcp_f32_e32 v176, v157
	v_exp_f32_e32 v157, v156
	v_add_f32_e32 v156, v48, v132
	v_mul_f32_e32 v156, 0xbfb8aa3b, v156
	v_exp_f32_e32 v156, v156
	v_add_f32_e32 v157, 1.0, v157
	v_rcp_f32_e32 v164, v157
	v_add_f32_e32 v157, v53, v129
	v_mul_f32_e32 v157, 0xbfb8aa3b, v157
	v_exp_f32_e32 v165, v157
	v_add_f32_e32 v157, v49, v133
	v_mul_f32_e32 v157, 0xbfb8aa3b, v157
	v_exp_f32_e32 v157, v157
	v_add_f32_e32 v165, 1.0, v165
	v_rcp_f32_e32 v165, v165
	v_cvt_pk_bf16_f32 v161, v162, v163
	v_pk_add_f32 v[156:157], v[156:157], 1.0 op_sel_hi:[1,0]
	s_nop 0
	v_rcp_f32_e32 v177, v156
	v_pk_mul_f32 v[164:165], v[164:165], v[156:157]
	v_add_f32_e32 v156, v54, v130
	v_mul_f32_e32 v156, 0xbfb8aa3b, v156
	v_rcp_f32_e32 v178, v157
	v_exp_f32_e32 v157, v156
	v_add_f32_e32 v156, v50, v134
	v_mul_f32_e32 v156, 0xbfb8aa3b, v156
	v_exp_f32_e32 v156, v156
	v_add_f32_e32 v157, 1.0, v157
	v_rcp_f32_e32 v166, v157
	v_add_f32_e32 v157, v55, v131
	v_mul_f32_e32 v157, 0xbfb8aa3b, v157
	v_exp_f32_e32 v167, v157
	v_add_f32_e32 v157, v51, v135
	v_mul_f32_e32 v157, 0xbfb8aa3b, v157
	v_exp_f32_e32 v157, v157
	v_add_f32_e32 v167, 1.0, v167
	v_rcp_f32_e32 v167, v167
	v_cvt_pk_bf16_f32 v162, v164, v165
	v_pk_add_f32 v[156:157], v[156:157], 1.0 op_sel_hi:[1,0]
	s_nop 0
	v_rcp_f32_e32 v179, v156
	v_pk_mul_f32 v[166:167], v[166:167], v[156:157]
	v_add_co_u32_e32 v156, vcc, s92, v158
	v_rcp_f32_e32 v180, v157
	v_cvt_pk_bf16_f32 v163, v166, v167
	v_addc_co_u32_e32 v157, vcc, 0, v159, vcc
	flat_store_dwordx4 v[156:157], v[160:163] nt
	v_add_co_u32_e32 v156, vcc, s93, v158
	s_nop 0
	v_cvt_pk_bf16_f32 v160, v148, v168
	v_add_f32_e32 v148, v44, v136
	v_mul_f32_e32 v148, 0xbfb8aa3b, v148
	v_exp_f32_e32 v148, v148
	v_cvt_pk_bf16_f32 v161, v169, v176
	v_cvt_pk_bf16_f32 v162, v177, v178
	v_cvt_pk_bf16_f32 v163, v179, v180
	v_addc_co_u32_e32 v157, vcc, 0, v159, vcc
	v_add_f32_e32 v148, 1.0, v148
	flat_store_dwordx4 v[156:157], v[160:163] nt
	v_add_f32_e32 v156, v40, v140
	v_add_f32_e32 v157, v41, v141
	v_rcp_f32_e32 v160, v148
	v_add_f32_e32 v148, v45, v137
	v_mul_f32_e32 v148, 0xbfb8aa3b, v148
	v_exp_f32_e32 v148, v148
	v_mul_f32_e32 v156, 0xbfb8aa3b, v156
	v_mul_f32_e32 v157, 0xbfb8aa3b, v157
	v_exp_f32_e32 v156, v156
	v_exp_f32_e32 v157, v157
	v_add_f32_e32 v148, 1.0, v148
	v_rcp_f32_e32 v161, v148
	v_pk_add_f32 v[156:157], v[156:157], 1.0 op_sel_hi:[1,0]
	s_nop 0
	v_rcp_f32_e32 v148, v156
	v_pk_mul_f32 v[160:161], v[160:161], v[156:157]
	v_add_f32_e32 v156, v46, v138
	v_mul_f32_e32 v156, 0xbfb8aa3b, v156
	v_rcp_f32_e32 v168, v157
	v_exp_f32_e32 v157, v156
	v_add_f32_e32 v156, v42, v142
	v_mul_f32_e32 v156, 0xbfb8aa3b, v156
	v_exp_f32_e32 v156, v156
	v_add_f32_e32 v157, 1.0, v157
	v_rcp_f32_e32 v162, v157
	v_add_f32_e32 v157, v47, v139
	v_mul_f32_e32 v157, 0xbfb8aa3b, v157
	v_exp_f32_e32 v163, v157
	v_add_f32_e32 v157, v43, v143
	v_mul_f32_e32 v157, 0xbfb8aa3b, v157
	v_exp_f32_e32 v157, v157
	v_add_f32_e32 v163, 1.0, v163
	v_rcp_f32_e32 v163, v163
	v_cvt_pk_bf16_f32 v160, v160, v161
	v_pk_add_f32 v[156:157], v[156:157], 1.0 op_sel_hi:[1,0]
	s_nop 0
	v_rcp_f32_e32 v169, v156
	v_pk_mul_f32 v[162:163], v[162:163], v[156:157]
	v_add_f32_e32 v156, v36, v128
	v_mul_f32_e32 v156, 0xbfb8aa3b, v156
	v_rcp_f32_e32 v176, v157
	v_exp_f32_e32 v157, v156
	v_add_f32_e32 v156, v32, v132
	v_mul_f32_e32 v156, 0xbfb8aa3b, v156
	v_exp_f32_e32 v156, v156
	v_add_f32_e32 v157, 1.0, v157
	v_rcp_f32_e32 v164, v157
	v_add_f32_e32 v157, v37, v129
	v_mul_f32_e32 v157, 0xbfb8aa3b, v157
	v_exp_f32_e32 v165, v157
	v_add_f32_e32 v157, v33, v133
	v_mul_f32_e32 v157, 0xbfb8aa3b, v157
	v_exp_f32_e32 v157, v157
	v_add_f32_e32 v165, 1.0, v165
	v_rcp_f32_e32 v165, v165
	v_cvt_pk_bf16_f32 v161, v162, v163
	v_pk_add_f32 v[156:157], v[156:157], 1.0 op_sel_hi:[1,0]
	s_nop 0
	v_rcp_f32_e32 v177, v156
	v_pk_mul_f32 v[164:165], v[164:165], v[156:157]
	v_add_f32_e32 v156, v38, v130
	v_mul_f32_e32 v156, 0xbfb8aa3b, v156
	v_rcp_f32_e32 v178, v157
	v_exp_f32_e32 v157, v156
	v_add_f32_e32 v156, v34, v134
	v_mul_f32_e32 v156, 0xbfb8aa3b, v156
	v_exp_f32_e32 v156, v156
	v_add_f32_e32 v157, 1.0, v157
	v_rcp_f32_e32 v166, v157
	v_add_f32_e32 v157, v39, v131
	v_mul_f32_e32 v157, 0xbfb8aa3b, v157
	v_exp_f32_e32 v167, v157
	v_add_f32_e32 v157, v35, v135
	v_mul_f32_e32 v157, 0xbfb8aa3b, v157
	v_exp_f32_e32 v157, v157
	v_add_f32_e32 v167, 1.0, v167
	v_rcp_f32_e32 v167, v167
	v_cvt_pk_bf16_f32 v162, v164, v165
	v_pk_add_f32 v[156:157], v[156:157], 1.0 op_sel_hi:[1,0]
	s_nop 0
	v_rcp_f32_e32 v179, v156
	v_pk_mul_f32 v[166:167], v[166:167], v[156:157]
	v_add_co_u32_e32 v156, vcc, s94, v158
	v_rcp_f32_e32 v180, v157
	v_cvt_pk_bf16_f32 v163, v166, v167
	v_addc_co_u32_e32 v157, vcc, 0, v159, vcc
	flat_store_dwordx4 v[156:157], v[160:163] nt
	v_add_co_u32_e32 v156, vcc, s95, v158
	s_nop 0
	v_cvt_pk_bf16_f32 v160, v148, v168
	v_add_f32_e32 v148, v28, v136
	v_mul_f32_e32 v148, 0xbfb8aa3b, v148
	v_exp_f32_e32 v148, v148
	v_cvt_pk_bf16_f32 v161, v169, v176
	v_cvt_pk_bf16_f32 v162, v177, v178
	v_cvt_pk_bf16_f32 v163, v179, v180
	v_addc_co_u32_e32 v157, vcc, 0, v159, vcc
	v_add_f32_e32 v148, 1.0, v148
	flat_store_dwordx4 v[156:157], v[160:163] nt
	v_add_f32_e32 v156, v24, v140
	v_add_f32_e32 v157, v25, v141
	v_rcp_f32_e32 v160, v148
	v_add_f32_e32 v148, v29, v137
	v_mul_f32_e32 v148, 0xbfb8aa3b, v148
	v_exp_f32_e32 v148, v148
	v_mul_f32_e32 v156, 0xbfb8aa3b, v156
	v_mul_f32_e32 v157, 0xbfb8aa3b, v157
	v_exp_f32_e32 v156, v156
	v_exp_f32_e32 v157, v157
	v_add_f32_e32 v148, 1.0, v148
	v_rcp_f32_e32 v161, v148
	v_add_f32_e32 v136, v12, v136
	v_pk_add_f32 v[156:157], v[156:157], 1.0 op_sel_hi:[1,0]
	v_mul_f32_e32 v136, 0xbfb8aa3b, v136
	v_rcp_f32_e32 v148, v156
	v_pk_mul_f32 v[160:161], v[160:161], v[156:157]
	v_add_f32_e32 v156, v30, v138
	v_mul_f32_e32 v156, 0xbfb8aa3b, v156
	v_rcp_f32_e32 v168, v157
	v_exp_f32_e32 v157, v156
	v_add_f32_e32 v156, v26, v142
	v_mul_f32_e32 v156, 0xbfb8aa3b, v156
	v_exp_f32_e32 v156, v156
	v_add_f32_e32 v157, 1.0, v157
	v_rcp_f32_e32 v162, v157
	v_add_f32_e32 v157, v31, v139
	v_mul_f32_e32 v157, 0xbfb8aa3b, v157
	v_exp_f32_e32 v163, v157
	v_add_f32_e32 v157, v27, v143
	v_mul_f32_e32 v157, 0xbfb8aa3b, v157
	v_exp_f32_e32 v157, v157
	v_add_f32_e32 v163, 1.0, v163
	v_rcp_f32_e32 v163, v163
	v_cvt_pk_bf16_f32 v160, v160, v161
	v_pk_add_f32 v[156:157], v[156:157], 1.0 op_sel_hi:[1,0]
	v_add_f32_e32 v137, v13, v137
	v_rcp_f32_e32 v169, v156
	v_pk_mul_f32 v[162:163], v[162:163], v[156:157]
	v_add_f32_e32 v156, v20, v128
	v_mul_f32_e32 v156, 0xbfb8aa3b, v156
	v_rcp_f32_e32 v176, v157
	v_exp_f32_e32 v157, v156
	v_add_f32_e32 v156, v16, v132
	v_mul_f32_e32 v156, 0xbfb8aa3b, v156
	v_exp_f32_e32 v156, v156
	v_add_f32_e32 v157, 1.0, v157
	v_rcp_f32_e32 v164, v157
	v_add_f32_e32 v157, v21, v129
	v_mul_f32_e32 v157, 0xbfb8aa3b, v157
	v_exp_f32_e32 v165, v157
	v_add_f32_e32 v157, v17, v133
	v_mul_f32_e32 v157, 0xbfb8aa3b, v157
	v_exp_f32_e32 v157, v157
	v_add_f32_e32 v165, 1.0, v165
	v_rcp_f32_e32 v165, v165
	v_cvt_pk_bf16_f32 v161, v162, v163
	v_pk_add_f32 v[156:157], v[156:157], 1.0 op_sel_hi:[1,0]
	v_mul_f32_e32 v137, 0xbfb8aa3b, v137
	v_rcp_f32_e32 v177, v156
	v_pk_mul_f32 v[164:165], v[164:165], v[156:157]
	v_add_f32_e32 v156, v22, v130
	v_mul_f32_e32 v156, 0xbfb8aa3b, v156
	v_rcp_f32_e32 v178, v157
	v_exp_f32_e32 v157, v156
	v_add_f32_e32 v156, v18, v134
	v_mul_f32_e32 v156, 0xbfb8aa3b, v156
	v_exp_f32_e32 v156, v156
	v_add_f32_e32 v157, 1.0, v157
	v_rcp_f32_e32 v166, v157
	v_add_f32_e32 v157, v23, v131
	v_mul_f32_e32 v157, 0xbfb8aa3b, v157
	v_exp_f32_e32 v167, v157
	v_add_f32_e32 v157, v19, v135
	v_mul_f32_e32 v157, 0xbfb8aa3b, v157
	v_exp_f32_e32 v157, v157
	v_add_f32_e32 v167, 1.0, v167
	v_rcp_f32_e32 v167, v167
	v_cvt_pk_bf16_f32 v162, v164, v165
	v_pk_add_f32 v[156:157], v[156:157], 1.0 op_sel_hi:[1,0]
	v_add_f32_e32 v128, v4, v128
	v_rcp_f32_e32 v179, v156
	v_pk_mul_f32 v[166:167], v[166:167], v[156:157]
	v_add_co_u32_e32 v156, vcc, s96, v158
	v_rcp_f32_e32 v180, v157
	v_cvt_pk_bf16_f32 v163, v166, v167
	v_addc_co_u32_e32 v157, vcc, 0, v159, vcc
	flat_store_dwordx4 v[156:157], v[160:163] nt
	v_add_co_u32_e32 v156, vcc, s97, v158
	s_nop 0
	v_cvt_pk_bf16_f32 v160, v148, v168
	v_exp_f32_e32 v148, v136
	v_add_f32_e32 v136, v8, v140
	v_mul_f32_e32 v136, 0xbfb8aa3b, v136
	v_exp_f32_e32 v136, v136
	v_add_f32_e32 v140, 1.0, v148
	v_exp_f32_e32 v148, v137
	v_add_f32_e32 v137, v9, v141
	v_mul_f32_e32 v137, 0xbfb8aa3b, v137
	v_exp_f32_e32 v137, v137
	v_add_f32_e32 v141, 1.0, v148
	v_rcp_f32_e32 v140, v140
	v_rcp_f32_e32 v141, v141
	v_pk_add_f32 v[136:137], v[136:137], 1.0 op_sel_hi:[1,0]
	v_cvt_pk_bf16_f32 v161, v169, v176
	v_rcp_f32_e32 v148, v136
	v_pk_mul_f32 v[140:141], v[140:141], v[136:137]
	v_add_f32_e32 v136, v14, v138
	v_cvt_pk_bf16_f32 v162, v177, v178
	v_cvt_pk_bf16_f32 v163, v179, v180
	v_addc_co_u32_e32 v157, vcc, 0, v159, vcc
	v_mul_f32_e32 v136, 0xbfb8aa3b, v136
	flat_store_dwordx4 v[156:157], v[160:163] nt
	v_rcp_f32_e32 v156, v137
	v_exp_f32_e32 v137, v136
	v_add_f32_e32 v136, v10, v142
	v_mul_f32_e32 v136, 0xbfb8aa3b, v136
	v_exp_f32_e32 v136, v136
	v_add_f32_e32 v137, 1.0, v137
	v_rcp_f32_e32 v138, v137
	v_add_f32_e32 v137, v15, v139
	v_mul_f32_e32 v137, 0xbfb8aa3b, v137
	v_exp_f32_e32 v139, v137
	v_add_f32_e32 v137, v11, v143
	v_mul_f32_e32 v137, 0xbfb8aa3b, v137
	v_exp_f32_e32 v137, v137
	v_add_f32_e32 v139, 1.0, v139
	v_rcp_f32_e32 v139, v139
	v_mul_f32_e32 v128, 0xbfb8aa3b, v128
	v_pk_add_f32 v[136:137], v[136:137], 1.0 op_sel_hi:[1,0]
	v_add_f32_e32 v129, v5, v129
	v_rcp_f32_e32 v142, v136
	v_pk_mul_f32 v[138:139], v[138:139], v[136:137]
	v_rcp_f32_e32 v136, v137
	v_exp_f32_e32 v137, v128
	v_mul_f32_e32 v129, 0xbfb8aa3b, v129
	v_add_f32_e32 v128, v0, v132
	v_mul_f32_e32 v128, 0xbfb8aa3b, v128
	v_add_f32_e32 v132, 1.0, v137
	v_exp_f32_e32 v137, v129
	v_add_f32_e32 v129, v1, v133
	v_mul_f32_e32 v129, 0xbfb8aa3b, v129
	v_exp_f32_e32 v128, v128
	v_exp_f32_e32 v129, v129
	v_add_f32_e32 v133, 1.0, v137
	v_rcp_f32_e32 v132, v132
	v_rcp_f32_e32 v133, v133
	v_pk_add_f32 v[128:129], v[128:129], 1.0 op_sel_hi:[1,0]
	s_nop 0
	v_rcp_f32_e32 v137, v128
	v_pk_mul_f32 v[132:133], v[132:133], v[128:129]
	v_add_f32_e32 v128, v6, v130
	v_mul_f32_e32 v128, 0xbfb8aa3b, v128
	v_rcp_f32_e32 v143, v129
	v_exp_f32_e32 v129, v128
	v_add_f32_e32 v128, v2, v134
	v_mul_f32_e32 v128, 0xbfb8aa3b, v128
	v_exp_f32_e32 v128, v128
	v_add_f32_e32 v129, 1.0, v129
	v_rcp_f32_e32 v130, v129
	v_add_f32_e32 v129, v7, v131
	v_mul_f32_e32 v129, 0xbfb8aa3b, v129
	v_exp_f32_e32 v131, v129
	v_add_f32_e32 v129, v3, v135
	v_mul_f32_e32 v129, 0xbfb8aa3b, v129
	v_exp_f32_e32 v129, v129
	v_add_f32_e32 v131, 1.0, v131
	v_rcp_f32_e32 v131, v131
	v_pk_add_f32 v[128:129], v[128:129], 1.0 op_sel_hi:[1,0]
	s_nop 0
	v_rcp_f32_e32 v157, v128
	v_rcp_f32_e32 v160, v129
	v_pk_mul_f32 v[134:135], v[130:131], v[128:129]
	v_cvt_pk_bf16_f32 v130, v132, v133
	v_add_co_u32_e32 v132, vcc, s12, v158
	v_cvt_pk_bf16_f32 v128, v140, v141
	v_cvt_pk_bf16_f32 v129, v138, v139
	v_cvt_pk_bf16_f32 v131, v134, v135
	v_addc_co_u32_e32 v133, vcc, 0, v159, vcc
	flat_store_dwordx4 v[132:133], v[128:131] nt
	v_add_co_u32_e32 v132, vcc, 0x161000, v158
	s_nop 0
	v_cvt_pk_bf16_f32 v128, v148, v156
	v_cvt_pk_bf16_f32 v129, v142, v136
	v_cvt_pk_bf16_f32 v130, v137, v143
	v_cvt_pk_bf16_f32 v131, v157, v160
	v_addc_co_u32_e32 v133, vcc, 0, v159, vcc
	flat_store_dwordx4 v[132:133], v[128:131] nt

.LBB0_196:
	s_lshl_b32 s6, s48, 7
	s_addk_i32 s6, 0xf800
	v_lshl_or_b32 v128, v130, 3, s6
	v_or_b32_e32 v148, s77, v128
	v_readlane_b32 s48, v254, 18
	v_lshlrev_b64 v[128:129], 2, v[148:149]
	v_readlane_b32 s58, v254, 28
	v_readlane_b32 s59, v254, 29
	v_lshl_add_u64 v[164:165], v[148:149], 1, s[2:3]
	v_lshlrev_b64 v[156:157], 13, v[156:157]
	v_lshl_add_u64 v[130:131], s[58:59], 0, v[128:129]
	v_lshl_add_u64 v[128:129], s[20:21], 0, v[128:129]
	global_load_dwordx4 v[140:143], v[130:131], off
	global_load_dwordx4 v[136:139], v[128:129], off
	global_load_dwordx4 v[132:135], v[130:131], off offset:16
	s_nop 0
	global_load_dwordx4 v[128:131], v[128:129], off offset:16
	v_lshl_add_u64 v[156:157], v[164:165], 0, v[156:157]
	v_readlane_b32 s49, v254, 19
	v_readlane_b32 s50, v254, 20
	v_readlane_b32 s51, v254, 21
	v_readlane_b32 s52, v254, 22
	v_readlane_b32 s53, v254, 23
	v_readlane_b32 s54, v254, 24
	v_readlane_b32 s55, v254, 25
	v_readlane_b32 s56, v254, 26
	v_readlane_b32 s57, v254, 27
	v_readlane_b32 s60, v254, 30
	v_readlane_b32 s61, v254, 31
	v_readlane_b32 s62, v254, 32
	v_readlane_b32 s63, v254, 33
	s_waitcnt vmcnt(0)
	v_add_f32_e32 v124, v124, v140
	v_add_f32_e32 v125, v125, v141
	v_add_f32_e32 v126, v126, v142
	v_add_f32_e32 v127, v127, v143
	v_add_f32_e32 v120, v120, v132
	v_add_f32_e32 v121, v121, v133
	v_add_f32_e32 v122, v122, v134
	v_add_f32_e32 v123, v123, v135
	v_mul_f32_e32 v124, 0xbfb8aa3b, v124
	v_mul_f32_e32 v125, 0xbfb8aa3b, v125
	v_mul_f32_e32 v126, 0xbfb8aa3b, v126
	v_mul_f32_e32 v127, 0xbfb8aa3b, v127
	v_mul_f32_e32 v120, 0xbfb8aa3b, v120
	v_mul_f32_e32 v121, 0xbfb8aa3b, v121
	v_mul_f32_e32 v122, 0xbfb8aa3b, v122
	v_mul_f32_e32 v123, 0xbfb8aa3b, v123
	v_exp_f32_e32 v124, v124
	v_exp_f32_e32 v125, v125
	v_exp_f32_e32 v126, v126
	v_exp_f32_e32 v127, v127
	v_exp_f32_e32 v120, v120
	v_exp_f32_e32 v121, v121
	v_exp_f32_e32 v122, v122
	v_exp_f32_e32 v123, v123
	v_add_f32_e32 v116, v116, v136
	v_add_f32_e32 v117, v117, v137
	v_add_f32_e32 v118, v118, v138
	v_add_f32_e32 v119, v119, v139
	v_add_f32_e32 v112, v112, v128
	v_add_f32_e32 v113, v113, v129
	v_add_f32_e32 v114, v114, v130
	v_add_f32_e32 v115, v115, v131
	v_mul_f32_e32 v116, 0xbfb8aa3b, v116
	v_mul_f32_e32 v117, 0xbfb8aa3b, v117
	v_mul_f32_e32 v118, 0xbfb8aa3b, v118
	v_mul_f32_e32 v119, 0xbfb8aa3b, v119
	v_mul_f32_e32 v148, 0xbfb8aa3b, v112
	v_mul_f32_e32 v166, 0xbfb8aa3b, v113
	v_mul_f32_e32 v167, 0xbfb8aa3b, v114
	v_mul_f32_e32 v168, 0xbfb8aa3b, v115
	v_add_f32_e32 v108, v108, v140
	v_add_f32_e32 v109, v109, v141
	v_exp_f32_e32 v112, v116
	v_exp_f32_e32 v113, v117
	v_exp_f32_e32 v114, v118
	v_exp_f32_e32 v115, v119
	v_exp_f32_e32 v116, v148
	v_exp_f32_e32 v117, v166
	v_exp_f32_e32 v118, v167
	v_exp_f32_e32 v119, v168
	v_mul_f32_e32 v108, 0xbfb8aa3b, v108
	v_mul_f32_e32 v109, 0xbfb8aa3b, v109
	v_add_f32_e32 v124, 1.0, v124
	v_add_f32_e32 v125, 1.0, v125
	v_add_f32_e32 v126, 1.0, v126
	v_add_f32_e32 v127, 1.0, v127
	v_add_f32_e32 v148, 1.0, v120
	v_add_f32_e32 v166, 1.0, v121
	v_add_f32_e32 v167, 1.0, v122
	v_add_f32_e32 v168, 1.0, v123
	v_exp_f32_e32 v108, v108
	v_exp_f32_e32 v109, v109
	v_rcp_f32_e32 v120, v124
	v_rcp_f32_e32 v121, v125
	v_rcp_f32_e32 v122, v126
	v_rcp_f32_e32 v123, v127
	v_rcp_f32_e32 v124, v148
	v_rcp_f32_e32 v125, v166
	v_rcp_f32_e32 v126, v167
	v_rcp_f32_e32 v127, v168
	v_add_f32_e32 v104, v104, v136
	v_add_f32_e32 v105, v105, v137
	v_pk_add_f32 v[112:113], v[112:113], 1.0 op_sel_hi:[1,0]
	v_pk_add_f32 v[114:115], v[114:115], 1.0 op_sel_hi:[1,0]
	v_pk_add_f32 v[116:117], v[116:117], 1.0 op_sel_hi:[1,0]
	v_pk_add_f32 v[118:119], v[118:119], 1.0 op_sel_hi:[1,0]
	v_mul_f32_e32 v104, 0xbfb8aa3b, v104
	v_mul_f32_e32 v105, 0xbfb8aa3b, v105
	v_rcp_f32_e32 v169, v112
	v_rcp_f32_e32 v176, v113
	v_rcp_f32_e32 v177, v114
	v_rcp_f32_e32 v178, v115
	v_rcp_f32_e32 v148, v116
	v_rcp_f32_e32 v166, v117
	v_rcp_f32_e32 v167, v118
	v_rcp_f32_e32 v168, v119
	v_exp_f32_e32 v104, v104
	v_add_f32_e32 v108, 1.0, v108
	v_exp_f32_e32 v105, v105
	v_add_f32_e32 v109, 1.0, v109
	v_pk_mul_f32 v[120:121], v[120:121], v[112:113]
	v_pk_mul_f32 v[122:123], v[122:123], v[114:115]
	v_pk_mul_f32 v[116:117], v[124:125], v[116:117]
	v_pk_mul_f32 v[118:119], v[126:127], v[118:119]
	v_rcp_f32_e32 v108, v108
	v_rcp_f32_e32 v109, v109
	v_cvt_pk_bf16_f32 v114, v120, v121
	v_cvt_pk_bf16_f32 v115, v122, v123
	v_cvt_pk_bf16_f32 v116, v116, v117
	v_cvt_pk_bf16_f32 v117, v118, v119
	flat_store_dwordx4 v[156:157], v[114:117] nt
	v_cvt_pk_bf16_f32 v112, v169, v176
	v_cvt_pk_bf16_f32 v113, v177, v178
	v_add_co_u32_e32 v116, vcc, s91, v156
	v_cvt_pk_bf16_f32 v114, v148, v166
	v_cvt_pk_bf16_f32 v115, v167, v168
	v_addc_co_u32_e32 v117, vcc, 0, v157, vcc
	v_pk_add_f32 v[104:105], v[104:105], 1.0 op_sel_hi:[1,0]
	flat_store_dwordx4 v[116:117], v[112:115] nt
	v_pk_mul_f32 v[108:109], v[108:109], v[104:105]
	v_add_f32_e32 v100, v100, v132
	v_rcp_f32_e32 v114, v104
	v_add_f32_e32 v104, v110, v142
	v_mul_f32_e32 v104, 0xbfb8aa3b, v104
	v_exp_f32_e32 v104, v104
	v_add_f32_e32 v101, v101, v133
	v_mul_f32_e32 v100, 0xbfb8aa3b, v100
	v_mul_f32_e32 v101, 0xbfb8aa3b, v101
	v_add_f32_e32 v104, 1.0, v104
	v_rcp_f32_e32 v110, v104
	v_add_f32_e32 v104, v111, v143
	v_mul_f32_e32 v104, 0xbfb8aa3b, v104
	v_exp_f32_e32 v104, v104
	v_exp_f32_e32 v100, v100
	v_exp_f32_e32 v101, v101
	v_add_f32_e32 v106, v106, v138
	v_add_f32_e32 v107, v107, v139
	v_add_f32_e32 v96, v96, v128
	v_add_f32_e32 v97, v97, v129
	v_mul_f32_e32 v106, 0xbfb8aa3b, v106
	v_mul_f32_e32 v107, 0xbfb8aa3b, v107
	v_mul_f32_e32 v96, 0xbfb8aa3b, v96
	v_mul_f32_e32 v97, 0xbfb8aa3b, v97
	v_exp_f32_e32 v106, v106
	v_exp_f32_e32 v107, v107
	v_add_f32_e32 v104, 1.0, v104
	v_exp_f32_e32 v96, v96
	v_add_f32_e32 v100, 1.0, v100
	v_exp_f32_e32 v97, v97
	v_add_f32_e32 v101, 1.0, v101
	v_rcp_f32_e32 v111, v104
	v_rcp_f32_e32 v100, v100
	v_rcp_f32_e32 v101, v101
	v_rcp_f32_e32 v115, v105
	v_pk_add_f32 v[104:105], v[106:107], 1.0 op_sel_hi:[1,0]
	v_pk_add_f32 v[96:97], v[96:97], 1.0 op_sel_hi:[1,0]
	v_pk_mul_f32 v[106:107], v[110:111], v[104:105]
	v_rcp_f32_e32 v111, v96
	v_pk_mul_f32 v[100:101], v[100:101], v[96:97]
	v_add_f32_e32 v96, v102, v134
	v_mul_f32_e32 v96, 0xbfb8aa3b, v96
	v_exp_f32_e32 v96, v96
	v_add_f32_e32 v98, v98, v130
	v_add_f32_e32 v99, v99, v131
	v_mul_f32_e32 v98, 0xbfb8aa3b, v98
	v_add_f32_e32 v96, 1.0, v96
	v_rcp_f32_e32 v102, v96
	v_add_f32_e32 v96, v103, v135
	v_mul_f32_e32 v96, 0xbfb8aa3b, v96
	v_exp_f32_e32 v96, v96
	v_mul_f32_e32 v99, 0xbfb8aa3b, v99
	v_add_f32_e32 v92, v92, v140
	v_add_f32_e32 v93, v93, v141
	v_exp_f32_e32 v98, v98
	v_exp_f32_e32 v99, v99
	v_mul_f32_e32 v92, 0xbfb8aa3b, v92
	v_mul_f32_e32 v93, 0xbfb8aa3b, v93
	v_exp_f32_e32 v92, v92
	v_exp_f32_e32 v93, v93
	v_add_f32_e32 v96, 1.0, v96
	v_rcp_f32_e32 v103, v96
	v_add_f32_e32 v88, v88, v136
	v_add_f32_e32 v89, v89, v137
	v_rcp_f32_e32 v117, v97
	v_pk_add_f32 v[96:97], v[98:99], 1.0 op_sel_hi:[1,0]
	v_mul_f32_e32 v88, 0xbfb8aa3b, v88
	v_mul_f32_e32 v89, 0xbfb8aa3b, v89
	v_rcp_f32_e32 v116, v104
	v_rcp_f32_e32 v110, v105
	v_rcp_f32_e32 v118, v96
	v_rcp_f32_e32 v119, v97
	v_exp_f32_e32 v88, v88
	v_add_f32_e32 v92, 1.0, v92
	v_exp_f32_e32 v89, v89
	v_add_f32_e32 v93, 1.0, v93
	v_lshlrev_b64 v[112:113], 13, v[162:163]
	v_rcp_f32_e32 v92, v92
	v_rcp_f32_e32 v93, v93
	v_pk_mul_f32 v[102:103], v[102:103], v[96:97]
	v_lshl_add_u64 v[104:105], v[164:165], 0, v[112:113]
	v_cvt_pk_bf16_f32 v96, v108, v109
	v_cvt_pk_bf16_f32 v97, v106, v107
	v_cvt_pk_bf16_f32 v98, v100, v101
	v_cvt_pk_bf16_f32 v99, v102, v103
	v_add_co_u32_e32 v100, vcc, s91, v104
	flat_store_dwordx4 v[104:105], v[96:99] nt
	s_nop 0
	v_addc_co_u32_e32 v101, vcc, 0, v105, vcc
	v_cvt_pk_bf16_f32 v96, v114, v115
	v_cvt_pk_bf16_f32 v97, v116, v110
	v_cvt_pk_bf16_f32 v98, v111, v117
	v_cvt_pk_bf16_f32 v99, v118, v119
	v_pk_add_f32 v[88:89], v[88:89], 1.0 op_sel_hi:[1,0]
	flat_store_dwordx4 v[100:101], v[96:99] nt
	v_pk_mul_f32 v[92:93], v[92:93], v[88:89]
	v_add_f32_e32 v84, v84, v132
	v_rcp_f32_e32 v98, v88
	v_add_f32_e32 v88, v94, v142
	v_mul_f32_e32 v88, 0xbfb8aa3b, v88
	v_exp_f32_e32 v88, v88
	v_add_f32_e32 v85, v85, v133
	v_mul_f32_e32 v84, 0xbfb8aa3b, v84
	v_mul_f32_e32 v85, 0xbfb8aa3b, v85
	v_add_f32_e32 v88, 1.0, v88
	v_rcp_f32_e32 v94, v88
	v_add_f32_e32 v88, v95, v143
	v_mul_f32_e32 v88, 0xbfb8aa3b, v88
	v_exp_f32_e32 v88, v88
	v_exp_f32_e32 v84, v84
	v_exp_f32_e32 v85, v85
	v_add_f32_e32 v90, v90, v138
	v_add_f32_e32 v91, v91, v139
	v_add_f32_e32 v80, v80, v128
	v_add_f32_e32 v81, v81, v129
	v_mul_f32_e32 v90, 0xbfb8aa3b, v90
	v_mul_f32_e32 v91, 0xbfb8aa3b, v91
	v_mul_f32_e32 v80, 0xbfb8aa3b, v80
	v_mul_f32_e32 v81, 0xbfb8aa3b, v81
	v_exp_f32_e32 v90, v90
	v_exp_f32_e32 v91, v91
	v_add_f32_e32 v88, 1.0, v88
	v_exp_f32_e32 v80, v80
	v_add_f32_e32 v84, 1.0, v84
	v_exp_f32_e32 v81, v81
	v_add_f32_e32 v85, 1.0, v85
	v_rcp_f32_e32 v95, v88
	v_rcp_f32_e32 v84, v84
	v_rcp_f32_e32 v85, v85
	v_rcp_f32_e32 v99, v89
	v_pk_add_f32 v[88:89], v[90:91], 1.0 op_sel_hi:[1,0]
	v_pk_add_f32 v[80:81], v[80:81], 1.0 op_sel_hi:[1,0]
	v_pk_mul_f32 v[90:91], v[94:95], v[88:89]
	v_rcp_f32_e32 v95, v80
	v_pk_mul_f32 v[84:85], v[84:85], v[80:81]
	v_add_f32_e32 v80, v86, v134
	v_mul_f32_e32 v80, 0xbfb8aa3b, v80
	v_exp_f32_e32 v80, v80
	v_add_f32_e32 v82, v82, v130
	v_add_f32_e32 v83, v83, v131
	v_mul_f32_e32 v82, 0xbfb8aa3b, v82
	v_add_f32_e32 v80, 1.0, v80
	v_rcp_f32_e32 v86, v80
	v_add_f32_e32 v80, v87, v135
	v_mul_f32_e32 v80, 0xbfb8aa3b, v80
	v_exp_f32_e32 v80, v80
	v_mul_f32_e32 v83, 0xbfb8aa3b, v83
	v_add_f32_e32 v76, v76, v140
	v_add_f32_e32 v77, v77, v141
	v_exp_f32_e32 v82, v82
	v_exp_f32_e32 v83, v83
	v_mul_f32_e32 v76, 0xbfb8aa3b, v76
	v_mul_f32_e32 v77, 0xbfb8aa3b, v77
	v_exp_f32_e32 v76, v76
	v_exp_f32_e32 v77, v77
	v_add_f32_e32 v80, 1.0, v80
	v_rcp_f32_e32 v87, v80
	v_add_f32_e32 v72, v72, v136
	v_add_f32_e32 v73, v73, v137
	v_rcp_f32_e32 v101, v81
	v_pk_add_f32 v[80:81], v[82:83], 1.0 op_sel_hi:[1,0]
	v_mul_f32_e32 v72, 0xbfb8aa3b, v72
	v_mul_f32_e32 v73, 0xbfb8aa3b, v73
	v_rcp_f32_e32 v100, v88
	v_rcp_f32_e32 v94, v89
	v_rcp_f32_e32 v102, v80
	v_rcp_f32_e32 v103, v81
	v_exp_f32_e32 v72, v72
	v_add_f32_e32 v76, 1.0, v76
	v_exp_f32_e32 v73, v73
	v_add_f32_e32 v77, 1.0, v77
	v_lshlrev_b64 v[96:97], 13, v[160:161]
	v_rcp_f32_e32 v76, v76
	v_rcp_f32_e32 v77, v77
	v_pk_mul_f32 v[86:87], v[86:87], v[80:81]
	v_lshl_add_u64 v[88:89], v[164:165], 0, v[96:97]
	v_cvt_pk_bf16_f32 v80, v92, v93
	v_cvt_pk_bf16_f32 v81, v90, v91
	v_cvt_pk_bf16_f32 v82, v84, v85
	v_cvt_pk_bf16_f32 v83, v86, v87
	v_add_co_u32_e32 v84, vcc, s91, v88
	flat_store_dwordx4 v[88:89], v[80:83] nt
	s_nop 0
	v_addc_co_u32_e32 v85, vcc, 0, v89, vcc
	v_cvt_pk_bf16_f32 v80, v98, v99
	v_cvt_pk_bf16_f32 v81, v100, v94
	v_cvt_pk_bf16_f32 v82, v95, v101
	v_cvt_pk_bf16_f32 v83, v102, v103
	v_pk_add_f32 v[72:73], v[72:73], 1.0 op_sel_hi:[1,0]
	flat_store_dwordx4 v[84:85], v[80:83] nt
	v_pk_mul_f32 v[76:77], v[76:77], v[72:73]
	v_add_f32_e32 v68, v68, v132
	v_rcp_f32_e32 v82, v72
	v_add_f32_e32 v72, v78, v142
	v_mul_f32_e32 v72, 0xbfb8aa3b, v72
	v_exp_f32_e32 v72, v72
	v_add_f32_e32 v69, v69, v133
	v_mul_f32_e32 v68, 0xbfb8aa3b, v68
	v_mul_f32_e32 v69, 0xbfb8aa3b, v69
	v_add_f32_e32 v72, 1.0, v72
	v_rcp_f32_e32 v78, v72
	v_add_f32_e32 v72, v79, v143
	v_mul_f32_e32 v72, 0xbfb8aa3b, v72
	v_exp_f32_e32 v72, v72
	v_exp_f32_e32 v68, v68
	v_exp_f32_e32 v69, v69
	v_add_f32_e32 v74, v74, v138
	v_add_f32_e32 v75, v75, v139
	v_add_f32_e32 v64, v64, v128
	v_add_f32_e32 v65, v65, v129
	v_mul_f32_e32 v74, 0xbfb8aa3b, v74
	v_mul_f32_e32 v75, 0xbfb8aa3b, v75
	v_mul_f32_e32 v64, 0xbfb8aa3b, v64
	v_mul_f32_e32 v65, 0xbfb8aa3b, v65
	v_exp_f32_e32 v74, v74
	v_exp_f32_e32 v75, v75
	v_add_f32_e32 v72, 1.0, v72
	v_exp_f32_e32 v64, v64
	v_add_f32_e32 v68, 1.0, v68
	v_exp_f32_e32 v65, v65
	v_add_f32_e32 v69, 1.0, v69
	v_rcp_f32_e32 v79, v72
	v_rcp_f32_e32 v68, v68
	v_rcp_f32_e32 v69, v69
	v_rcp_f32_e32 v83, v73
	v_pk_add_f32 v[72:73], v[74:75], 1.0 op_sel_hi:[1,0]
	v_pk_add_f32 v[64:65], v[64:65], 1.0 op_sel_hi:[1,0]
	v_pk_mul_f32 v[74:75], v[78:79], v[72:73]
	v_rcp_f32_e32 v79, v64
	v_pk_mul_f32 v[68:69], v[68:69], v[64:65]
	v_add_f32_e32 v64, v70, v134
	v_mul_f32_e32 v64, 0xbfb8aa3b, v64
	v_exp_f32_e32 v64, v64
	v_add_f32_e32 v66, v66, v130
	v_add_f32_e32 v67, v67, v131
	v_mul_f32_e32 v66, 0xbfb8aa3b, v66
	v_add_f32_e32 v64, 1.0, v64
	v_rcp_f32_e32 v70, v64
	v_add_f32_e32 v64, v71, v135
	v_mul_f32_e32 v64, 0xbfb8aa3b, v64
	v_exp_f32_e32 v64, v64
	v_mul_f32_e32 v67, 0xbfb8aa3b, v67
	v_add_f32_e32 v60, v60, v140
	v_add_f32_e32 v61, v61, v141
	v_exp_f32_e32 v66, v66
	v_exp_f32_e32 v67, v67
	v_mul_f32_e32 v60, 0xbfb8aa3b, v60
	v_mul_f32_e32 v61, 0xbfb8aa3b, v61
	v_exp_f32_e32 v60, v60
	v_exp_f32_e32 v61, v61
	v_add_f32_e32 v64, 1.0, v64
	v_rcp_f32_e32 v71, v64
	v_add_f32_e32 v56, v56, v136
	v_add_f32_e32 v57, v57, v137
	v_rcp_f32_e32 v85, v65
	v_pk_add_f32 v[64:65], v[66:67], 1.0 op_sel_hi:[1,0]
	v_mul_f32_e32 v56, 0xbfb8aa3b, v56
	v_mul_f32_e32 v57, 0xbfb8aa3b, v57
	v_rcp_f32_e32 v84, v72
	v_rcp_f32_e32 v78, v73
	v_rcp_f32_e32 v86, v64
	v_rcp_f32_e32 v87, v65
	v_exp_f32_e32 v56, v56
	v_add_f32_e32 v60, 1.0, v60
	v_exp_f32_e32 v57, v57
	v_add_f32_e32 v61, 1.0, v61
	v_lshlrev_b64 v[80:81], 13, v[158:159]
	v_rcp_f32_e32 v60, v60
	v_rcp_f32_e32 v61, v61
	v_pk_mul_f32 v[70:71], v[70:71], v[64:65]
	v_lshl_add_u64 v[72:73], v[164:165], 0, v[80:81]
	v_cvt_pk_bf16_f32 v64, v76, v77
	v_cvt_pk_bf16_f32 v65, v74, v75
	v_cvt_pk_bf16_f32 v66, v68, v69
	v_cvt_pk_bf16_f32 v67, v70, v71
	v_add_co_u32_e32 v68, vcc, s91, v72
	flat_store_dwordx4 v[72:73], v[64:67] nt
	s_nop 0
	v_addc_co_u32_e32 v69, vcc, 0, v73, vcc
	v_cvt_pk_bf16_f32 v64, v82, v83
	v_cvt_pk_bf16_f32 v65, v84, v78
	v_cvt_pk_bf16_f32 v66, v79, v85
	v_cvt_pk_bf16_f32 v67, v86, v87
	v_pk_add_f32 v[56:57], v[56:57], 1.0 op_sel_hi:[1,0]
	flat_store_dwordx4 v[68:69], v[64:67] nt
	v_pk_mul_f32 v[60:61], v[60:61], v[56:57]
	v_add_f32_e32 v52, v52, v132
	v_rcp_f32_e32 v64, v56
	v_add_f32_e32 v56, v62, v142
	v_mul_f32_e32 v56, 0xbfb8aa3b, v56
	v_exp_f32_e32 v56, v56
	v_add_f32_e32 v53, v53, v133
	v_mul_f32_e32 v52, 0xbfb8aa3b, v52
	v_mul_f32_e32 v53, 0xbfb8aa3b, v53
	v_add_f32_e32 v56, 1.0, v56
	v_rcp_f32_e32 v62, v56
	v_add_f32_e32 v56, v63, v143
	v_mul_f32_e32 v56, 0xbfb8aa3b, v56
	v_exp_f32_e32 v56, v56
	v_exp_f32_e32 v52, v52
	v_exp_f32_e32 v53, v53
	v_add_f32_e32 v58, v58, v138
	v_add_f32_e32 v59, v59, v139
	v_add_f32_e32 v48, v48, v128
	v_add_f32_e32 v49, v49, v129
	v_mul_f32_e32 v58, 0xbfb8aa3b, v58
	v_mul_f32_e32 v59, 0xbfb8aa3b, v59
	v_mul_f32_e32 v48, 0xbfb8aa3b, v48
	v_mul_f32_e32 v49, 0xbfb8aa3b, v49
	v_exp_f32_e32 v58, v58
	v_exp_f32_e32 v59, v59
	v_add_f32_e32 v56, 1.0, v56
	v_exp_f32_e32 v48, v48
	v_add_f32_e32 v52, 1.0, v52
	v_exp_f32_e32 v49, v49
	v_add_f32_e32 v53, 1.0, v53
	v_rcp_f32_e32 v63, v56
	v_rcp_f32_e32 v52, v52
	v_rcp_f32_e32 v53, v53
	v_rcp_f32_e32 v65, v57
	v_pk_add_f32 v[56:57], v[58:59], 1.0 op_sel_hi:[1,0]
	v_pk_add_f32 v[48:49], v[48:49], 1.0 op_sel_hi:[1,0]
	v_rcp_f32_e32 v66, v56
	v_pk_mul_f32 v[58:59], v[62:63], v[56:57]
	v_rcp_f32_e32 v56, v57
	v_rcp_f32_e32 v57, v48
	v_pk_mul_f32 v[52:53], v[52:53], v[48:49]
	v_add_f32_e32 v48, v54, v134
	v_mul_f32_e32 v48, 0xbfb8aa3b, v48
	v_exp_f32_e32 v48, v48
	v_add_f32_e32 v50, v50, v130
	v_add_f32_e32 v51, v51, v131
	v_mul_f32_e32 v50, 0xbfb8aa3b, v50
	v_add_f32_e32 v48, 1.0, v48
	v_rcp_f32_e32 v54, v48
	v_add_f32_e32 v48, v55, v135
	v_mul_f32_e32 v48, 0xbfb8aa3b, v48
	v_exp_f32_e32 v48, v48
	v_mul_f32_e32 v51, 0xbfb8aa3b, v51
	v_add_f32_e32 v44, v44, v140
	v_add_f32_e32 v45, v45, v141
	v_exp_f32_e32 v50, v50
	v_exp_f32_e32 v51, v51
	v_mul_f32_e32 v44, 0xbfb8aa3b, v44
	v_mul_f32_e32 v45, 0xbfb8aa3b, v45
	v_add_f32_e32 v48, 1.0, v48
	v_exp_f32_e32 v44, v44
	v_exp_f32_e32 v45, v45
	v_rcp_f32_e32 v55, v48
	v_add_f32_e32 v40, v40, v136
	v_add_f32_e32 v41, v41, v137
	v_rcp_f32_e32 v62, v49
	v_pk_add_f32 v[48:49], v[50:51], 1.0 op_sel_hi:[1,0]
	v_mul_f32_e32 v40, 0xbfb8aa3b, v40
	v_mul_f32_e32 v41, 0xbfb8aa3b, v41
	v_rcp_f32_e32 v63, v48
	v_rcp_f32_e32 v67, v49
	v_exp_f32_e32 v40, v40
	v_add_f32_e32 v44, 1.0, v44
	v_exp_f32_e32 v41, v41
	v_add_f32_e32 v45, 1.0, v45
	v_pk_mul_f32 v[54:55], v[54:55], v[48:49]
	v_cvt_pk_bf16_f32 v50, v52, v53
	v_add_co_u32_e32 v52, vcc, s92, v156
	v_rcp_f32_e32 v44, v44
	v_rcp_f32_e32 v45, v45
	v_cvt_pk_bf16_f32 v48, v60, v61
	v_cvt_pk_bf16_f32 v49, v58, v59
	v_cvt_pk_bf16_f32 v51, v54, v55
	v_addc_co_u32_e32 v53, vcc, 0, v157, vcc
	flat_store_dwordx4 v[52:53], v[48:51] nt
	v_add_co_u32_e32 v52, vcc, s93, v156
	s_nop 0
	v_cvt_pk_bf16_f32 v48, v64, v65
	v_cvt_pk_bf16_f32 v49, v66, v56
	v_cvt_pk_bf16_f32 v50, v57, v62
	v_cvt_pk_bf16_f32 v51, v63, v67
	v_addc_co_u32_e32 v53, vcc, 0, v157, vcc
	v_pk_add_f32 v[40:41], v[40:41], 1.0 op_sel_hi:[1,0]
	flat_store_dwordx4 v[52:53], v[48:51] nt
	v_pk_mul_f32 v[44:45], v[44:45], v[40:41]
	v_add_f32_e32 v36, v36, v132
	v_rcp_f32_e32 v48, v40
	v_add_f32_e32 v40, v46, v142
	v_mul_f32_e32 v40, 0xbfb8aa3b, v40
	v_exp_f32_e32 v40, v40
	v_add_f32_e32 v37, v37, v133
	v_mul_f32_e32 v36, 0xbfb8aa3b, v36
	v_mul_f32_e32 v37, 0xbfb8aa3b, v37
	v_add_f32_e32 v40, 1.0, v40
	v_rcp_f32_e32 v46, v40
	v_add_f32_e32 v40, v47, v143
	v_mul_f32_e32 v40, 0xbfb8aa3b, v40
	v_exp_f32_e32 v40, v40
	v_exp_f32_e32 v36, v36
	v_exp_f32_e32 v37, v37
	v_add_f32_e32 v42, v42, v138
	v_add_f32_e32 v43, v43, v139
	v_add_f32_e32 v32, v32, v128
	v_add_f32_e32 v33, v33, v129
	v_mul_f32_e32 v42, 0xbfb8aa3b, v42
	v_mul_f32_e32 v43, 0xbfb8aa3b, v43
	v_mul_f32_e32 v32, 0xbfb8aa3b, v32
	v_mul_f32_e32 v33, 0xbfb8aa3b, v33
	v_exp_f32_e32 v42, v42
	v_exp_f32_e32 v43, v43
	v_add_f32_e32 v40, 1.0, v40
	v_exp_f32_e32 v32, v32
	v_add_f32_e32 v36, 1.0, v36
	v_exp_f32_e32 v33, v33
	v_add_f32_e32 v37, 1.0, v37
	v_rcp_f32_e32 v47, v40
	v_rcp_f32_e32 v36, v36
	v_rcp_f32_e32 v37, v37
	v_rcp_f32_e32 v49, v41
	v_pk_add_f32 v[40:41], v[42:43], 1.0 op_sel_hi:[1,0]
	v_pk_add_f32 v[32:33], v[32:33], 1.0 op_sel_hi:[1,0]
	v_rcp_f32_e32 v50, v40
	v_pk_mul_f32 v[42:43], v[46:47], v[40:41]
	v_rcp_f32_e32 v40, v41
	v_rcp_f32_e32 v41, v32
	v_pk_mul_f32 v[36:37], v[36:37], v[32:33]
	v_add_f32_e32 v32, v38, v134
	v_mul_f32_e32 v32, 0xbfb8aa3b, v32
	v_exp_f32_e32 v32, v32
	v_add_f32_e32 v34, v34, v130
	v_add_f32_e32 v35, v35, v131
	v_mul_f32_e32 v34, 0xbfb8aa3b, v34
	v_add_f32_e32 v32, 1.0, v32
	v_rcp_f32_e32 v38, v32
	v_add_f32_e32 v32, v39, v135
	v_mul_f32_e32 v32, 0xbfb8aa3b, v32
	v_exp_f32_e32 v32, v32
	v_mul_f32_e32 v35, 0xbfb8aa3b, v35
	v_add_f32_e32 v28, v28, v140
	v_add_f32_e32 v29, v29, v141
	v_exp_f32_e32 v34, v34
	v_exp_f32_e32 v35, v35
	v_mul_f32_e32 v28, 0xbfb8aa3b, v28
	v_mul_f32_e32 v29, 0xbfb8aa3b, v29
	v_add_f32_e32 v32, 1.0, v32
	v_exp_f32_e32 v28, v28
	v_exp_f32_e32 v29, v29
	v_rcp_f32_e32 v39, v32
	v_add_f32_e32 v24, v24, v136
	v_add_f32_e32 v25, v25, v137
	v_rcp_f32_e32 v46, v33
	v_pk_add_f32 v[32:33], v[34:35], 1.0 op_sel_hi:[1,0]
	v_mul_f32_e32 v24, 0xbfb8aa3b, v24
	v_mul_f32_e32 v25, 0xbfb8aa3b, v25
	v_rcp_f32_e32 v47, v32
	v_rcp_f32_e32 v51, v33
	v_exp_f32_e32 v24, v24
	v_add_f32_e32 v28, 1.0, v28
	v_exp_f32_e32 v25, v25
	v_add_f32_e32 v29, 1.0, v29
	v_pk_mul_f32 v[38:39], v[38:39], v[32:33]
	v_cvt_pk_bf16_f32 v34, v36, v37
	v_add_co_u32_e32 v36, vcc, s94, v156
	v_rcp_f32_e32 v28, v28
	v_rcp_f32_e32 v29, v29
	v_cvt_pk_bf16_f32 v32, v44, v45
	v_cvt_pk_bf16_f32 v33, v42, v43
	v_cvt_pk_bf16_f32 v35, v38, v39
	v_addc_co_u32_e32 v37, vcc, 0, v157, vcc
	flat_store_dwordx4 v[36:37], v[32:35] nt
	v_add_co_u32_e32 v36, vcc, s95, v156
	s_nop 0
	v_cvt_pk_bf16_f32 v32, v48, v49
	v_cvt_pk_bf16_f32 v33, v50, v40
	v_cvt_pk_bf16_f32 v34, v41, v46
	v_cvt_pk_bf16_f32 v35, v47, v51
	v_addc_co_u32_e32 v37, vcc, 0, v157, vcc
	v_pk_add_f32 v[24:25], v[24:25], 1.0 op_sel_hi:[1,0]
	flat_store_dwordx4 v[36:37], v[32:35] nt
	v_pk_mul_f32 v[28:29], v[28:29], v[24:25]
	v_add_f32_e32 v20, v20, v132
	v_rcp_f32_e32 v32, v24
	v_add_f32_e32 v24, v30, v142
	v_mul_f32_e32 v24, 0xbfb8aa3b, v24
	v_exp_f32_e32 v24, v24
	v_add_f32_e32 v21, v21, v133
	v_mul_f32_e32 v20, 0xbfb8aa3b, v20
	v_mul_f32_e32 v21, 0xbfb8aa3b, v21
	v_add_f32_e32 v24, 1.0, v24
	v_rcp_f32_e32 v30, v24
	v_add_f32_e32 v24, v31, v143
	v_mul_f32_e32 v24, 0xbfb8aa3b, v24
	v_exp_f32_e32 v24, v24
	v_exp_f32_e32 v20, v20
	v_exp_f32_e32 v21, v21
	v_add_f32_e32 v26, v26, v138
	v_add_f32_e32 v27, v27, v139
	v_add_f32_e32 v16, v16, v128
	v_add_f32_e32 v17, v17, v129
	v_mul_f32_e32 v26, 0xbfb8aa3b, v26
	v_mul_f32_e32 v27, 0xbfb8aa3b, v27
	v_mul_f32_e32 v16, 0xbfb8aa3b, v16
	v_mul_f32_e32 v17, 0xbfb8aa3b, v17
	v_exp_f32_e32 v26, v26
	v_exp_f32_e32 v27, v27
	v_add_f32_e32 v24, 1.0, v24
	v_exp_f32_e32 v16, v16
	v_add_f32_e32 v20, 1.0, v20
	v_exp_f32_e32 v17, v17
	v_add_f32_e32 v21, 1.0, v21
	v_rcp_f32_e32 v31, v24
	v_rcp_f32_e32 v20, v20
	v_rcp_f32_e32 v21, v21
	v_rcp_f32_e32 v33, v25
	v_pk_add_f32 v[24:25], v[26:27], 1.0 op_sel_hi:[1,0]
	v_pk_add_f32 v[16:17], v[16:17], 1.0 op_sel_hi:[1,0]
	v_rcp_f32_e32 v34, v24
	v_pk_mul_f32 v[26:27], v[30:31], v[24:25]
	v_rcp_f32_e32 v24, v25
	v_rcp_f32_e32 v25, v16
	v_pk_mul_f32 v[20:21], v[20:21], v[16:17]
	v_add_f32_e32 v16, v22, v134
	v_mul_f32_e32 v16, 0xbfb8aa3b, v16
	v_exp_f32_e32 v16, v16
	v_add_f32_e32 v18, v18, v130
	v_add_f32_e32 v19, v19, v131
	v_mul_f32_e32 v18, 0xbfb8aa3b, v18
	v_add_f32_e32 v16, 1.0, v16
	v_rcp_f32_e32 v22, v16
	v_add_f32_e32 v16, v23, v135
	v_mul_f32_e32 v16, 0xbfb8aa3b, v16
	v_exp_f32_e32 v16, v16
	v_mul_f32_e32 v19, 0xbfb8aa3b, v19
	v_add_f32_e32 v12, v12, v140
	v_add_f32_e32 v13, v13, v141
	v_exp_f32_e32 v18, v18
	v_exp_f32_e32 v19, v19
	v_mul_f32_e32 v12, 0xbfb8aa3b, v12
	v_mul_f32_e32 v13, 0xbfb8aa3b, v13
	v_add_f32_e32 v16, 1.0, v16
	v_exp_f32_e32 v12, v12
	v_exp_f32_e32 v13, v13
	v_rcp_f32_e32 v23, v16
	v_add_f32_e32 v8, v8, v136
	v_add_f32_e32 v9, v9, v137
	v_rcp_f32_e32 v30, v17
	v_pk_add_f32 v[16:17], v[18:19], 1.0 op_sel_hi:[1,0]
	v_mul_f32_e32 v8, 0xbfb8aa3b, v8
	v_mul_f32_e32 v9, 0xbfb8aa3b, v9
	v_rcp_f32_e32 v31, v16
	v_rcp_f32_e32 v35, v17
	v_exp_f32_e32 v8, v8
	v_add_f32_e32 v12, 1.0, v12
	v_exp_f32_e32 v9, v9
	v_add_f32_e32 v13, 1.0, v13
	v_pk_mul_f32 v[22:23], v[22:23], v[16:17]
	v_cvt_pk_bf16_f32 v18, v20, v21
	v_add_co_u32_e32 v20, vcc, s96, v156
	v_rcp_f32_e32 v12, v12
	v_rcp_f32_e32 v13, v13
	v_cvt_pk_bf16_f32 v16, v28, v29
	v_cvt_pk_bf16_f32 v17, v26, v27
	v_cvt_pk_bf16_f32 v19, v22, v23
	v_addc_co_u32_e32 v21, vcc, 0, v157, vcc
	flat_store_dwordx4 v[20:21], v[16:19] nt
	v_add_co_u32_e32 v20, vcc, s97, v156
	s_nop 0
	v_cvt_pk_bf16_f32 v16, v32, v33
	v_cvt_pk_bf16_f32 v17, v34, v24
	v_cvt_pk_bf16_f32 v18, v25, v30
	v_cvt_pk_bf16_f32 v19, v31, v35
	v_addc_co_u32_e32 v21, vcc, 0, v157, vcc
	v_pk_add_f32 v[8:9], v[8:9], 1.0 op_sel_hi:[1,0]
	flat_store_dwordx4 v[20:21], v[16:19] nt
	v_pk_mul_f32 v[12:13], v[12:13], v[8:9]
	v_add_f32_e32 v4, v4, v132
	v_rcp_f32_e32 v16, v8
	v_add_f32_e32 v8, v14, v142
	v_mul_f32_e32 v8, 0xbfb8aa3b, v8
	v_exp_f32_e32 v8, v8
	v_add_f32_e32 v5, v5, v133
	v_mul_f32_e32 v4, 0xbfb8aa3b, v4
	v_mul_f32_e32 v5, 0xbfb8aa3b, v5
	v_add_f32_e32 v8, 1.0, v8
	v_rcp_f32_e32 v14, v8
	v_add_f32_e32 v8, v15, v143
	v_mul_f32_e32 v8, 0xbfb8aa3b, v8
	v_exp_f32_e32 v8, v8
	v_exp_f32_e32 v4, v4
	v_exp_f32_e32 v5, v5
	v_add_f32_e32 v10, v10, v138
	v_add_f32_e32 v11, v11, v139
	v_add_f32_e32 v0, v0, v128
	v_add_f32_e32 v1, v1, v129
	v_mul_f32_e32 v10, 0xbfb8aa3b, v10
	v_mul_f32_e32 v11, 0xbfb8aa3b, v11
	v_mul_f32_e32 v0, 0xbfb8aa3b, v0
	v_mul_f32_e32 v1, 0xbfb8aa3b, v1
	v_exp_f32_e32 v10, v10
	v_exp_f32_e32 v11, v11
	v_add_f32_e32 v8, 1.0, v8
	v_exp_f32_e32 v0, v0
	v_add_f32_e32 v4, 1.0, v4
	v_exp_f32_e32 v1, v1
	v_add_f32_e32 v5, 1.0, v5
	v_rcp_f32_e32 v15, v8
	v_rcp_f32_e32 v4, v4
	v_rcp_f32_e32 v5, v5
	v_rcp_f32_e32 v17, v9
	v_pk_add_f32 v[8:9], v[10:11], 1.0 op_sel_hi:[1,0]
	v_pk_add_f32 v[0:1], v[0:1], 1.0 op_sel_hi:[1,0]
	v_rcp_f32_e32 v18, v8
	v_pk_mul_f32 v[10:11], v[14:15], v[8:9]
	v_rcp_f32_e32 v8, v9
	v_rcp_f32_e32 v9, v0
	v_pk_mul_f32 v[4:5], v[4:5], v[0:1]
	v_add_f32_e32 v0, v6, v134
	v_mul_f32_e32 v0, 0xbfb8aa3b, v0
	v_exp_f32_e32 v0, v0
	v_add_f32_e32 v2, v2, v130
	v_add_f32_e32 v3, v3, v131
	v_mul_f32_e32 v2, 0xbfb8aa3b, v2
	v_add_f32_e32 v0, 1.0, v0
	v_rcp_f32_e32 v6, v0
	v_add_f32_e32 v0, v7, v135
	v_mul_f32_e32 v0, 0xbfb8aa3b, v0
	v_exp_f32_e32 v0, v0
	v_mul_f32_e32 v3, 0xbfb8aa3b, v3
	v_exp_f32_e32 v2, v2
	v_exp_f32_e32 v3, v3
	v_add_f32_e32 v0, 1.0, v0
	v_rcp_f32_e32 v7, v0
	v_rcp_f32_e32 v14, v1
	v_pk_add_f32 v[0:1], v[2:3], 1.0 op_sel_hi:[1,0]
	v_cvt_pk_bf16_f32 v2, v4, v5
	v_rcp_f32_e32 v15, v0
	v_rcp_f32_e32 v19, v1
	v_pk_mul_f32 v[6:7], v[6:7], v[0:1]
	v_add_co_u32_e32 v4, vcc, s12, v156
	v_cvt_pk_bf16_f32 v0, v12, v13
	v_cvt_pk_bf16_f32 v1, v10, v11
	v_cvt_pk_bf16_f32 v3, v6, v7
	v_addc_co_u32_e32 v5, vcc, 0, v157, vcc
	flat_store_dwordx4 v[4:5], v[0:3] nt
	v_add_co_u32_e32 v4, vcc, 0x161000, v156
	s_nop 0
	v_cvt_pk_bf16_f32 v0, v16, v17
	v_cvt_pk_bf16_f32 v1, v18, v8
	v_cvt_pk_bf16_f32 v2, v9, v14
	v_cvt_pk_bf16_f32 v3, v15, v19
	v_addc_co_u32_e32 v5, vcc, 0, v157, vcc
	flat_store_dwordx4 v[4:5], v[0:3] nt
	s_and_b64 vcc, exec, s[10:11]
	s_cbranch_vccnz .LBB0_142

.LBB0_992:
	v_mov_b32_e32 v138, v192
	s_lshl_b32 s2, s2, 8
	s_lshl_b32 s3, s3, 8
	v_lshrrev_b32_e32 v139, 1, v138
	s_add_i32 s2, s2, s54
	v_and_or_b32 v139, v139, 24, s3
	v_and_or_b32 v150, v138, 15, s2
	v_or_b32_e32 v140, s55, v139
	s_cmp_lg_u32 s66, 0
	v_ashrrev_i32_e32 v151, 31, v150
	s_cselect_b64 s[2:3], -1, 0
	s_cmp_eq_u32 s66, 0
	v_ashrrev_i32_e32 v141, 31, v140
	v_lshlrev_b64 v[146:147], 13, v[150:151]
	v_or_b32_e32 v144, 16, v150
	v_or_b32_e32 v142, 32, v150
	v_or_b32_e32 v138, 48, v150
	s_cbranch_scc1 .LBB0_1000
	v_readlane_b32 s44, v254, 49
	v_readlane_b32 s45, v254, 50
	v_lshlrev_b64 v[148:149], 1, v[140:141]
	v_ashrrev_i32_e32 v145, 31, v144
	v_lshl_add_u64 v[154:155], s[44:45], 0, v[146:147]
	v_lshl_add_u64 v[158:159], v[154:155], 0, v[148:149]
	v_add_co_u32_e32 v154, vcc, 0x1000, v158
	v_lshlrev_b64 v[162:163], 13, v[144:145]
	s_nop 0
	v_addc_co_u32_e32 v155, vcc, 0, v159, vcc
	v_lshl_add_u64 v[158:159], v[158:159], 0, s[24:25]
	v_lshl_add_u64 v[162:163], s[44:45], 0, v[162:163]
	global_load_dwordx4 v[154:157], v[154:155], off nt
	v_lshl_add_u64 v[166:167], v[162:163], 0, v[148:149]
	global_load_dwordx4 v[158:161], v[158:159], off offset:256 nt
	v_add_co_u32_e32 v162, vcc, s60, v166
	v_ashrrev_i32_e32 v143, 31, v142
	s_nop 0
	v_addc_co_u32_e32 v163, vcc, 0, v167, vcc
	global_load_dwordx4 v[162:165], v[162:163], off nt
	v_readlane_b32 s42, v254, 45
	v_ashrrev_i32_e32 v139, 31, v138
	v_lshlrev_b64 v[170:171], 12, v[150:151]
	v_lshlrev_b64 v[172:173], 13, v[142:143]
	v_readlane_b32 s43, v254, 46
	v_lshl_add_u64 v[166:167], v[166:167], 0, s[24:25]
	v_lshlrev_b64 v[174:175], 13, v[138:139]
	v_lshl_add_u64 v[170:171], s[42:43], 0, v[170:171]
	v_lshl_add_u64 v[172:173], s[44:45], 0, v[172:173]
	global_load_dwordx4 v[166:169], v[166:167], off offset:256 nt
	v_lshl_add_u64 v[174:175], s[44:45], 0, v[174:175]
	v_lshl_add_u64 v[188:189], v[170:171], 0, v[148:149]
	v_lshl_add_u64 v[170:171], v[172:173], 0, v[148:149]
	v_lshl_add_u64 v[178:179], v[174:175], 0, v[148:149]
	v_lshl_add_u64 v[174:175], v[170:171], 0, s[24:25]
	v_add_co_u32_e32 v170, vcc, s60, v170
	global_load_dwordx4 v[174:177], v[174:175], off offset:256 nt
	s_nop 0
	v_addc_co_u32_e32 v171, vcc, 0, v171, vcc
	global_load_dwordx4 v[170:173], v[170:171], off nt
	v_lshl_add_u64 v[182:183], v[178:179], 0, s[24:25]
	v_add_co_u32_e32 v178, vcc, s60, v178
	v_lshlrev_b64 v[186:187], 12, v[144:145]
	s_nop 0
	v_addc_co_u32_e32 v179, vcc, 0, v179, vcc
	global_load_dwordx4 v[178:181], v[178:179], off nt
	s_nop 0
	global_load_dwordx4 v[182:185], v[182:183], off offset:256 nt
	s_waitcnt vmcnt(0)
	v_lshlrev_b32_e32 v190, 16, v154
	v_and_b32_e32 v191, 0xffff0000, v154
	v_lshlrev_b32_e32 v194, 16, v156
	v_and_b32_e32 v195, 0xffff0000, v156
	v_lshlrev_b32_e32 v154, 16, v155
	v_and_b32_e32 v155, 0xffff0000, v155
	v_lshlrev_b32_e32 v156, 16, v157
	v_and_b32_e32 v157, 0xffff0000, v157
	v_lshlrev_b32_e32 v196, 16, v158
	v_and_b32_e32 v197, 0xffff0000, v158
	v_lshlrev_b32_e32 v158, 16, v159
	v_and_b32_e32 v159, 0xffff0000, v159
	v_lshlrev_b32_e32 v198, 16, v160
	v_and_b32_e32 v199, 0xffff0000, v160
	v_lshlrev_b32_e32 v160, 16, v161
	v_and_b32_e32 v161, 0xffff0000, v161
	v_pk_mul_f32 v[190:191], v[124:125], v[190:191]
	v_pk_mul_f32 v[194:195], v[120:121], v[194:195]
	v_pk_mul_f32 v[200:201], v[126:127], v[154:155]
	v_pk_mul_f32 v[202:203], v[122:123], v[156:157]
	v_pk_mul_f32 v[196:197], v[92:93], v[196:197]
	v_pk_mul_f32 v[204:205], v[94:95], v[158:159]
	v_pk_mul_f32 v[198:199], v[88:89], v[198:199]
	v_pk_mul_f32 v[206:207], v[90:91], v[160:161]
	v_cvt_pk_bf16_f32 v154, v190, v191
	v_cvt_pk_bf16_f32 v155, v200, v201
	v_cvt_pk_bf16_f32 v156, v194, v195
	v_cvt_pk_bf16_f32 v157, v202, v203
	v_cvt_pk_bf16_f32 v158, v196, v197
	v_cvt_pk_bf16_f32 v159, v204, v205
	v_cvt_pk_bf16_f32 v160, v198, v199
	v_cvt_pk_bf16_f32 v161, v206, v207
	v_lshlrev_b32_e32 v190, 16, v162
	v_and_b32_e32 v191, 0xffff0000, v162
	global_store_dwordx4 v[188:189], v[154:157], off
	global_store_dwordx4 v[188:189], v[158:161], off offset:256
	v_lshlrev_b32_e32 v162, 16, v169
	v_pk_mul_f32 v[154:155], v[116:117], v[190:191]
	v_lshlrev_b32_e32 v158, 16, v163
	v_and_b32_e32 v159, 0xffff0000, v163
	v_lshlrev_b32_e32 v156, 16, v164
	v_and_b32_e32 v157, 0xffff0000, v164
	v_pk_mul_f32 v[158:159], v[118:119], v[158:159]
	v_lshlrev_b32_e32 v160, 16, v165
	v_and_b32_e32 v161, 0xffff0000, v165
	v_pk_mul_f32 v[156:157], v[112:113], v[156:157]
	v_pk_mul_f32 v[160:161], v[114:115], v[160:161]
	v_cvt_pk_bf16_f32 v154, v154, v155
	v_cvt_pk_bf16_f32 v155, v158, v159
	v_lshl_add_u64 v[158:159], s[42:43], 0, v[186:187]
	v_cvt_pk_bf16_f32 v156, v156, v157
	v_cvt_pk_bf16_f32 v157, v160, v161
	v_lshl_add_u64 v[158:159], v[158:159], 0, v[148:149]
	global_store_dwordx4 v[158:159], v[154:157], off
	v_lshlrev_b32_e32 v160, 16, v167
	v_and_b32_e32 v161, 0xffff0000, v167
	v_lshlrev_b32_e32 v154, 16, v166
	v_and_b32_e32 v155, 0xffff0000, v166
	v_lshlrev_b32_e32 v156, 16, v168
	v_and_b32_e32 v157, 0xffff0000, v168
	v_and_b32_e32 v163, 0xffff0000, v169
	v_pk_mul_f32 v[154:155], v[84:85], v[154:155]
	v_pk_mul_f32 v[156:157], v[80:81], v[156:157]
	v_pk_mul_f32 v[160:161], v[86:87], v[160:161]
	v_pk_mul_f32 v[162:163], v[82:83], v[162:163]
	v_cvt_pk_bf16_f32 v154, v154, v155
	v_cvt_pk_bf16_f32 v155, v160, v161
	v_cvt_pk_bf16_f32 v156, v156, v157
	v_cvt_pk_bf16_f32 v157, v162, v163
	global_store_dwordx4 v[158:159], v[154:157], off offset:256
	v_lshlrev_b64 v[158:159], 12, v[142:143]
	v_lshlrev_b32_e32 v160, 16, v171
	v_lshlrev_b32_e32 v154, 16, v170
	v_and_b32_e32 v155, 0xffff0000, v170
	v_lshlrev_b32_e32 v156, 16, v172
	v_and_b32_e32 v157, 0xffff0000, v172
	v_and_b32_e32 v161, 0xffff0000, v171
	v_lshlrev_b32_e32 v162, 16, v173
	v_and_b32_e32 v163, 0xffff0000, v173
	v_pk_mul_f32 v[154:155], v[108:109], v[154:155]
	v_pk_mul_f32 v[156:157], v[104:105], v[156:157]
	v_pk_mul_f32 v[160:161], v[110:111], v[160:161]
	v_pk_mul_f32 v[162:163], v[106:107], v[162:163]
	v_lshl_add_u64 v[158:159], s[42:43], 0, v[158:159]
	v_cvt_pk_bf16_f32 v154, v154, v155
	v_cvt_pk_bf16_f32 v155, v160, v161
	v_cvt_pk_bf16_f32 v156, v156, v157
	v_cvt_pk_bf16_f32 v157, v162, v163
	v_lshl_add_u64 v[158:159], v[158:159], 0, v[148:149]
	global_store_dwordx4 v[158:159], v[154:157], off
	v_lshlrev_b32_e32 v160, 16, v175
	v_and_b32_e32 v161, 0xffff0000, v175
	v_lshlrev_b32_e32 v154, 16, v174
	v_and_b32_e32 v155, 0xffff0000, v174
	v_lshlrev_b32_e32 v156, 16, v176
	v_and_b32_e32 v157, 0xffff0000, v176
	v_lshlrev_b32_e32 v162, 16, v177
	v_and_b32_e32 v163, 0xffff0000, v177
	v_pk_mul_f32 v[154:155], v[76:77], v[154:155]
	v_pk_mul_f32 v[156:157], v[72:73], v[156:157]
	v_pk_mul_f32 v[160:161], v[78:79], v[160:161]
	v_pk_mul_f32 v[162:163], v[74:75], v[162:163]
	v_cvt_pk_bf16_f32 v154, v154, v155
	v_cvt_pk_bf16_f32 v155, v160, v161
	v_cvt_pk_bf16_f32 v156, v156, v157
	v_cvt_pk_bf16_f32 v157, v162, v163
	global_store_dwordx4 v[158:159], v[154:157], off offset:256
	v_lshlrev_b64 v[158:159], 12, v[138:139]
	v_lshlrev_b32_e32 v160, 16, v179
	v_lshlrev_b32_e32 v154, 16, v178
	v_and_b32_e32 v155, 0xffff0000, v178
	v_lshlrev_b32_e32 v156, 16, v180
	v_and_b32_e32 v157, 0xffff0000, v180
	v_and_b32_e32 v161, 0xffff0000, v179
	v_lshlrev_b32_e32 v162, 16, v181
	v_and_b32_e32 v163, 0xffff0000, v181
	v_pk_mul_f32 v[154:155], v[100:101], v[154:155]
	v_pk_mul_f32 v[156:157], v[96:97], v[156:157]
	v_pk_mul_f32 v[160:161], v[102:103], v[160:161]
	v_pk_mul_f32 v[162:163], v[98:99], v[162:163]
	v_lshl_add_u64 v[158:159], s[42:43], 0, v[158:159]
	v_cvt_pk_bf16_f32 v154, v154, v155
	v_cvt_pk_bf16_f32 v155, v160, v161
	v_cvt_pk_bf16_f32 v156, v156, v157
	v_cvt_pk_bf16_f32 v157, v162, v163
	v_lshl_add_u64 v[158:159], v[158:159], 0, v[148:149]
	global_store_dwordx4 v[158:159], v[154:157], off
	v_lshlrev_b32_e32 v160, 16, v183
	v_and_b32_e32 v161, 0xffff0000, v183
	v_lshlrev_b32_e32 v154, 16, v182
	v_and_b32_e32 v155, 0xffff0000, v182
	v_lshlrev_b32_e32 v156, 16, v184
	v_and_b32_e32 v157, 0xffff0000, v184
	v_lshlrev_b32_e32 v162, 16, v185
	v_and_b32_e32 v163, 0xffff0000, v185
	v_pk_mul_f32 v[154:155], v[68:69], v[154:155]
	v_pk_mul_f32 v[156:157], v[64:65], v[156:157]
	v_pk_mul_f32 v[160:161], v[70:71], v[160:161]
	v_pk_mul_f32 v[162:163], v[66:67], v[162:163]
	v_cvt_pk_bf16_f32 v154, v154, v155
	v_cvt_pk_bf16_f32 v155, v160, v161
	v_cvt_pk_bf16_f32 v156, v156, v157
	v_cvt_pk_bf16_f32 v157, v162, v163
	global_store_dwordx4 v[158:159], v[154:157], off offset:256
	v_add_u32_e32 v170, 0x80, v150
	v_ashrrev_i32_e32 v171, 31, v170
	v_lshlrev_b64 v[154:155], 13, v[170:171]
	v_lshl_add_u64 v[154:155], s[44:45], 0, v[154:155]
	v_add_u32_e32 v172, 0x90, v150
	v_lshl_add_u64 v[158:159], v[154:155], 0, v[148:149]
	v_ashrrev_i32_e32 v173, 31, v172
	v_add_co_u32_e32 v154, vcc, s60, v158
	v_lshlrev_b64 v[162:163], 13, v[172:173]
	s_nop 0
	v_addc_co_u32_e32 v155, vcc, 0, v159, vcc
	v_lshl_add_u64 v[162:163], s[44:45], 0, v[162:163]
	global_load_dwordx4 v[154:157], v[154:155], off nt
	v_lshl_add_u64 v[158:159], v[158:159], 0, s[24:25]
	v_lshl_add_u64 v[166:167], v[162:163], 0, v[148:149]
	global_load_dwordx4 v[158:161], v[158:159], off offset:256 nt
	v_add_co_u32_e32 v162, vcc, s60, v166
	v_add_u32_e32 v186, 0xa0, v150
	s_nop 0
	v_addc_co_u32_e32 v163, vcc, 0, v167, vcc
	global_load_dwordx4 v[162:165], v[162:163], off nt
	v_ashrrev_i32_e32 v187, 31, v186
	v_lshlrev_b64 v[174:175], 13, v[186:187]
	v_lshl_add_u64 v[166:167], v[166:167], 0, s[24:25]
	v_lshlrev_b64 v[170:171], 12, v[170:171]
	v_lshlrev_b64 v[188:189], 12, v[172:173]
	v_lshl_add_u64 v[172:173], s[44:45], 0, v[174:175]
	v_add_u32_e32 v150, 0xb0, v150
	global_load_dwordx4 v[166:169], v[166:167], off offset:256 nt
	v_lshl_add_u64 v[170:171], s[42:43], 0, v[170:171]
	v_lshl_add_u64 v[172:173], v[172:173], 0, v[148:149]
	v_ashrrev_i32_e32 v151, 31, v150
	v_lshl_add_u64 v[190:191], v[170:171], 0, v[148:149]
	v_add_co_u32_e32 v170, vcc, s60, v172
	v_lshlrev_b64 v[176:177], 13, v[150:151]
	s_nop 0
	v_addc_co_u32_e32 v171, vcc, 0, v173, vcc
	v_lshl_add_u64 v[174:175], s[44:45], 0, v[176:177]
	v_lshl_add_u64 v[176:177], v[172:173], 0, s[24:25]
	global_load_dwordx4 v[170:173], v[170:171], off nt
	v_lshl_add_u64 v[174:175], v[174:175], 0, v[148:149]
	v_add_co_u32_e32 v178, vcc, s60, v174
	v_lshl_add_u64 v[182:183], v[174:175], 0, s[24:25]
	s_nop 0
	v_addc_co_u32_e32 v179, vcc, 0, v175, vcc
	global_load_dwordx4 v[174:177], v[176:177], off offset:256 nt
	s_nop 0
	global_load_dwordx4 v[178:181], v[178:179], off nt
	s_nop 0
	global_load_dwordx4 v[182:185], v[182:183], off offset:256 nt
	v_lshlrev_b64 v[150:151], 12, v[150:151]
	v_lshl_add_u64 v[150:151], s[42:43], 0, v[150:151]
	s_waitcnt vmcnt(7)
	v_lshlrev_b32_e32 v194, 16, v154
	v_and_b32_e32 v195, 0xffff0000, v154
	v_lshlrev_b32_e32 v196, 16, v156
	v_and_b32_e32 v197, 0xffff0000, v156
	v_lshlrev_b32_e32 v154, 16, v155
	v_and_b32_e32 v155, 0xffff0000, v155
	v_lshlrev_b32_e32 v156, 16, v157
	v_and_b32_e32 v157, 0xffff0000, v157
	s_waitcnt vmcnt(6)
	v_lshlrev_b32_e32 v198, 16, v158
	v_and_b32_e32 v199, 0xffff0000, v158
	v_lshlrev_b32_e32 v200, 16, v160
	v_and_b32_e32 v201, 0xffff0000, v160
	v_lshlrev_b32_e32 v158, 16, v159
	v_and_b32_e32 v159, 0xffff0000, v159
	v_lshlrev_b32_e32 v160, 16, v161
	v_and_b32_e32 v161, 0xffff0000, v161
	v_pk_mul_f32 v[194:195], v[60:61], v[194:195]
	v_pk_mul_f32 v[196:197], v[56:57], v[196:197]
	v_pk_mul_f32 v[206:207], v[62:63], v[154:155]
	v_pk_mul_f32 v[208:209], v[58:59], v[156:157]
	v_pk_mul_f32 v[198:199], v[28:29], v[198:199]
	v_pk_mul_f32 v[200:201], v[24:25], v[200:201]
	v_pk_mul_f32 v[210:211], v[30:31], v[158:159]
	v_pk_mul_f32 v[212:213], v[26:27], v[160:161]
	v_cvt_pk_bf16_f32 v154, v194, v195
	v_cvt_pk_bf16_f32 v155, v206, v207
	v_cvt_pk_bf16_f32 v156, v196, v197
	v_cvt_pk_bf16_f32 v157, v208, v209
	v_cvt_pk_bf16_f32 v158, v198, v199
	v_cvt_pk_bf16_f32 v159, v210, v211
	v_cvt_pk_bf16_f32 v160, v200, v201
	v_cvt_pk_bf16_f32 v161, v212, v213
	global_store_dwordx4 v[190:191], v[154:157], off
	global_store_dwordx4 v[190:191], v[158:161], off offset:256
	s_waitcnt vmcnt(7)
	v_lshlrev_b32_e32 v202, 16, v162
	v_lshlrev_b32_e32 v154, 16, v163
	v_and_b32_e32 v155, 0xffff0000, v163
	v_and_b32_e32 v203, 0xffff0000, v162
	v_lshlrev_b32_e32 v204, 16, v164
	v_and_b32_e32 v205, 0xffff0000, v164
	v_pk_mul_f32 v[158:159], v[54:55], v[154:155]
	v_lshlrev_b32_e32 v154, 16, v165
	v_and_b32_e32 v155, 0xffff0000, v165
	v_pk_mul_f32 v[202:203], v[52:53], v[202:203]
	v_pk_mul_f32 v[156:157], v[48:49], v[204:205]
	v_pk_mul_f32 v[160:161], v[50:51], v[154:155]
	v_cvt_pk_bf16_f32 v155, v158, v159
	v_lshl_add_u64 v[158:159], s[42:43], 0, v[188:189]
	v_cvt_pk_bf16_f32 v154, v202, v203
	v_cvt_pk_bf16_f32 v156, v156, v157
	v_cvt_pk_bf16_f32 v157, v160, v161
	v_lshl_add_u64 v[158:159], v[158:159], 0, v[148:149]
	global_store_dwordx4 v[158:159], v[154:157], off
	s_waitcnt vmcnt(7)
	v_lshlrev_b32_e32 v160, 16, v167
	v_and_b32_e32 v161, 0xffff0000, v167
	v_lshlrev_b32_e32 v154, 16, v166
	v_and_b32_e32 v155, 0xffff0000, v166
	v_lshlrev_b32_e32 v156, 16, v168
	v_and_b32_e32 v157, 0xffff0000, v168
	v_lshlrev_b32_e32 v162, 16, v169
	v_and_b32_e32 v163, 0xffff0000, v169
	v_pk_mul_f32 v[154:155], v[20:21], v[154:155]
	v_pk_mul_f32 v[156:157], v[16:17], v[156:157]
	v_pk_mul_f32 v[160:161], v[22:23], v[160:161]
	v_pk_mul_f32 v[162:163], v[18:19], v[162:163]
	v_cvt_pk_bf16_f32 v154, v154, v155
	v_cvt_pk_bf16_f32 v155, v160, v161
	v_cvt_pk_bf16_f32 v156, v156, v157
	v_cvt_pk_bf16_f32 v157, v162, v163
	global_store_dwordx4 v[158:159], v[154:157], off offset:256
	v_lshlrev_b64 v[158:159], 12, v[186:187]
	s_waitcnt vmcnt(7)
	v_lshlrev_b32_e32 v160, 16, v171
	v_lshlrev_b32_e32 v154, 16, v170
	v_and_b32_e32 v155, 0xffff0000, v170
	v_lshlrev_b32_e32 v156, 16, v172
	v_and_b32_e32 v157, 0xffff0000, v172
	v_and_b32_e32 v161, 0xffff0000, v171
	v_lshlrev_b32_e32 v162, 16, v173
	v_and_b32_e32 v163, 0xffff0000, v173
	v_pk_mul_f32 v[154:155], v[44:45], v[154:155]
	v_pk_mul_f32 v[156:157], v[40:41], v[156:157]
	v_pk_mul_f32 v[160:161], v[46:47], v[160:161]
	v_pk_mul_f32 v[162:163], v[42:43], v[162:163]
	v_lshl_add_u64 v[158:159], s[42:43], 0, v[158:159]
	v_cvt_pk_bf16_f32 v154, v154, v155
	v_cvt_pk_bf16_f32 v155, v160, v161
	v_cvt_pk_bf16_f32 v156, v156, v157
	v_cvt_pk_bf16_f32 v157, v162, v163
	v_lshl_add_u64 v[158:159], v[158:159], 0, v[148:149]
	global_store_dwordx4 v[158:159], v[154:157], off
	s_waitcnt vmcnt(7)
	v_lshlrev_b32_e32 v160, 16, v175
	v_and_b32_e32 v161, 0xffff0000, v175
	v_lshlrev_b32_e32 v154, 16, v174
	v_and_b32_e32 v155, 0xffff0000, v174
	v_lshlrev_b32_e32 v156, 16, v176
	v_and_b32_e32 v157, 0xffff0000, v176
	v_lshlrev_b32_e32 v162, 16, v177
	v_and_b32_e32 v163, 0xffff0000, v177
	v_pk_mul_f32 v[154:155], v[12:13], v[154:155]
	v_pk_mul_f32 v[156:157], v[8:9], v[156:157]
	v_pk_mul_f32 v[160:161], v[14:15], v[160:161]
	v_pk_mul_f32 v[162:163], v[10:11], v[162:163]
	v_cvt_pk_bf16_f32 v154, v154, v155
	v_cvt_pk_bf16_f32 v155, v160, v161
	v_cvt_pk_bf16_f32 v156, v156, v157
	v_cvt_pk_bf16_f32 v157, v162, v163
	global_store_dwordx4 v[158:159], v[154:157], off offset:256
	s_waitcnt vmcnt(7)
	v_lshlrev_b32_e32 v158, 16, v179
	v_and_b32_e32 v159, 0xffff0000, v179
	v_lshlrev_b32_e32 v154, 16, v178
	v_and_b32_e32 v155, 0xffff0000, v178
	v_lshlrev_b32_e32 v156, 16, v180
	v_and_b32_e32 v157, 0xffff0000, v180
	v_lshlrev_b32_e32 v160, 16, v181
	v_and_b32_e32 v161, 0xffff0000, v181
	v_pk_mul_f32 v[154:155], v[36:37], v[154:155]
	v_pk_mul_f32 v[156:157], v[32:33], v[156:157]
	v_pk_mul_f32 v[158:159], v[38:39], v[158:159]
	v_pk_mul_f32 v[160:161], v[34:35], v[160:161]
	v_cvt_pk_bf16_f32 v154, v154, v155
	v_cvt_pk_bf16_f32 v155, v158, v159
	v_cvt_pk_bf16_f32 v156, v156, v157
	v_cvt_pk_bf16_f32 v157, v160, v161
	v_lshl_add_u64 v[158:159], v[150:151], 0, v[148:149]
	global_store_dwordx4 v[158:159], v[154:157], off
	s_waitcnt vmcnt(7)
	v_lshlrev_b32_e32 v148, 16, v182
	v_and_b32_e32 v149, 0xffff0000, v182
	v_lshlrev_b32_e32 v150, 16, v184
	v_and_b32_e32 v151, 0xffff0000, v184
	v_lshlrev_b32_e32 v154, 16, v183
	v_and_b32_e32 v155, 0xffff0000, v183
	v_lshlrev_b32_e32 v156, 16, v185
	v_and_b32_e32 v157, 0xffff0000, v185
	v_pk_mul_f32 v[148:149], v[4:5], v[148:149]
	v_pk_mul_f32 v[150:151], v[0:1], v[150:151]
	v_pk_mul_f32 v[154:155], v[6:7], v[154:155]
	v_pk_mul_f32 v[156:157], v[2:3], v[156:157]
	v_cvt_pk_bf16_f32 v148, v148, v149
	v_cvt_pk_bf16_f32 v149, v154, v155
	v_cvt_pk_bf16_f32 v150, v150, v151
	v_cvt_pk_bf16_f32 v151, v156, v157
	global_store_dwordx4 v[158:159], v[148:151], off offset:256
	s_cbranch_execnz .LBB0_995
.LBB0_994:
	v_readlane_b32 s42, v254, 49
	v_readlane_b32 s43, v254, 50
	v_ashrrev_i32_e32 v145, 31, v144
	v_ashrrev_i32_e32 v143, 31, v142
	v_lshl_add_u64 v[150:151], v[140:141], 1, s[42:43]
	v_lshl_add_u64 v[140:141], v[150:151], 0, v[146:147]
	v_lshlrev_b64 v[144:145], 13, v[144:145]
	v_lshlrev_b64 v[142:143], 13, v[142:143]
	global_load_dwordx4 v[146:149], v[140:141], off nt
	global_load_dwordx4 v[154:157], v[140:141], off offset:256 nt
	v_lshl_add_u64 v[144:145], v[150:151], 0, v[144:145]
	v_lshl_add_u64 v[166:167], v[150:151], 0, v[142:143]
	global_load_dwordx4 v[158:161], v[144:145], off nt
	global_load_dwordx4 v[162:165], v[144:145], off offset:256 nt
	s_nop 0
	global_load_dwordx4 v[142:145], v[166:167], off nt
	s_nop 0
	global_load_dwordx4 v[166:169], v[166:167], off offset:256 nt
	v_ashrrev_i32_e32 v139, 31, v138
	v_lshlrev_b64 v[138:139], 13, v[138:139]
	v_lshl_add_u64 v[138:139], v[150:151], 0, v[138:139]
	global_load_dwordx4 v[170:173], v[138:139], off nt
	global_load_dwordx4 v[174:177], v[138:139], off offset:256 nt
	s_waitcnt vmcnt(0)
	v_lshlrev_b32_e32 v138, 16, v146
	v_and_b32_e32 v139, 0xffff0000, v146
	v_pk_mul_f32 v[124:125], v[124:125], v[138:139]
	v_lshlrev_b32_e32 v138, 16, v158
	v_and_b32_e32 v139, 0xffff0000, v158
	v_pk_mul_f32 v[116:117], v[116:117], v[138:139]
	v_lshlrev_b32_e32 v138, 16, v167
	v_and_b32_e32 v139, 0xffff0000, v167
	v_pk_mul_f32 v[78:79], v[78:79], v[138:139]
	v_lshlrev_b32_e32 v138, 16, v169
	v_and_b32_e32 v139, 0xffff0000, v169
	v_pk_mul_f32 v[74:75], v[74:75], v[138:139]
	v_lshlrev_b32_e32 v138, 16, v170
	v_and_b32_e32 v139, 0xffff0000, v170
	v_pk_mul_f32 v[100:101], v[100:101], v[138:139]
	v_lshlrev_b32_e32 v138, 16, v172
	v_and_b32_e32 v139, 0xffff0000, v172
	v_pk_mul_f32 v[96:97], v[96:97], v[138:139]
	v_lshlrev_b32_e32 v138, 16, v171
	v_and_b32_e32 v139, 0xffff0000, v171
	v_pk_mul_f32 v[102:103], v[102:103], v[138:139]
	v_lshlrev_b32_e32 v138, 16, v173
	v_and_b32_e32 v139, 0xffff0000, v173
	v_pk_mul_f32 v[98:99], v[98:99], v[138:139]
	v_lshlrev_b32_e32 v138, 16, v174
	v_and_b32_e32 v139, 0xffff0000, v174
	v_pk_mul_f32 v[68:69], v[68:69], v[138:139]
	v_lshlrev_b32_e32 v138, 16, v176
	v_and_b32_e32 v139, 0xffff0000, v176
	v_lshlrev_b32_e32 v150, 16, v148
	v_and_b32_e32 v151, 0xffff0000, v148
	v_lshlrev_b32_e32 v146, 16, v147
	v_and_b32_e32 v147, 0xffff0000, v147
	v_lshlrev_b32_e32 v148, 16, v149
	v_and_b32_e32 v149, 0xffff0000, v149
	v_lshlrev_b32_e32 v178, 16, v154
	v_and_b32_e32 v179, 0xffff0000, v154
	v_lshlrev_b32_e32 v180, 16, v156
	v_and_b32_e32 v181, 0xffff0000, v156
	v_lshlrev_b32_e32 v154, 16, v155
	v_and_b32_e32 v155, 0xffff0000, v155
	v_lshlrev_b32_e32 v156, 16, v157
	v_and_b32_e32 v157, 0xffff0000, v157
	v_pk_mul_f32 v[64:65], v[64:65], v[138:139]
	v_lshlrev_b32_e32 v138, 16, v175
	v_and_b32_e32 v139, 0xffff0000, v175
	v_pk_mul_f32 v[120:121], v[120:121], v[150:151]
	v_pk_mul_f32 v[126:127], v[126:127], v[146:147]
	v_pk_mul_f32 v[122:123], v[122:123], v[148:149]
	v_pk_mul_f32 v[92:93], v[92:93], v[178:179]
	v_pk_mul_f32 v[88:89], v[88:89], v[180:181]
	v_pk_mul_f32 v[94:95], v[94:95], v[154:155]
	v_pk_mul_f32 v[90:91], v[90:91], v[156:157]
	v_lshlrev_b32_e32 v146, 16, v160
	v_and_b32_e32 v147, 0xffff0000, v160
	v_lshlrev_b32_e32 v148, 16, v159
	v_and_b32_e32 v149, 0xffff0000, v159
	v_lshlrev_b32_e32 v150, 16, v161
	v_and_b32_e32 v151, 0xffff0000, v161
	v_lshlrev_b32_e32 v154, 16, v162
	v_and_b32_e32 v155, 0xffff0000, v162
	v_lshlrev_b32_e32 v156, 16, v164
	v_and_b32_e32 v157, 0xffff0000, v164
	v_lshlrev_b32_e32 v158, 16, v163
	v_and_b32_e32 v159, 0xffff0000, v163
	v_lshlrev_b32_e32 v160, 16, v165
	v_and_b32_e32 v161, 0xffff0000, v165
	v_lshlrev_b32_e32 v162, 16, v142
	v_and_b32_e32 v163, 0xffff0000, v142
	v_lshlrev_b32_e32 v164, 16, v144
	v_and_b32_e32 v165, 0xffff0000, v144
	v_lshlrev_b32_e32 v142, 16, v143
	v_and_b32_e32 v143, 0xffff0000, v143
	v_lshlrev_b32_e32 v144, 16, v145
	v_and_b32_e32 v145, 0xffff0000, v145
	v_lshlrev_b32_e32 v178, 16, v166
	v_and_b32_e32 v179, 0xffff0000, v166
	v_lshlrev_b32_e32 v180, 16, v168
	v_and_b32_e32 v181, 0xffff0000, v168
	v_pk_mul_f32 v[70:71], v[70:71], v[138:139]
	v_lshlrev_b32_e32 v138, 16, v177
	v_and_b32_e32 v139, 0xffff0000, v177
	v_pk_mul_f32 v[112:113], v[112:113], v[146:147]
	v_pk_mul_f32 v[118:119], v[118:119], v[148:149]
	v_pk_mul_f32 v[114:115], v[114:115], v[150:151]
	v_pk_mul_f32 v[84:85], v[84:85], v[154:155]
	v_pk_mul_f32 v[80:81], v[80:81], v[156:157]
	v_pk_mul_f32 v[86:87], v[86:87], v[158:159]
	v_pk_mul_f32 v[82:83], v[82:83], v[160:161]
	v_pk_mul_f32 v[108:109], v[108:109], v[162:163]
	v_pk_mul_f32 v[104:105], v[104:105], v[164:165]
	v_pk_mul_f32 v[110:111], v[110:111], v[142:143]
	v_pk_mul_f32 v[106:107], v[106:107], v[144:145]
	v_pk_mul_f32 v[76:77], v[76:77], v[178:179]
	v_pk_mul_f32 v[72:73], v[72:73], v[180:181]
	v_pk_mul_f32 v[66:67], v[66:67], v[138:139]
	v_add_co_u32_e32 v138, vcc, s61, v140
	s_mov_b32 s31, 0x100000
	s_nop 0
	v_addc_co_u32_e32 v139, vcc, 0, v141, vcc
	global_load_dwordx4 v[142:145], v[138:139], off nt
	v_add_co_u32_e32 v138, vcc, s62, v140
	s_mov_b64 s[42:43], 0x100000
	s_nop 0
	v_addc_co_u32_e32 v139, vcc, 0, v141, vcc
	global_load_dwordx4 v[146:149], v[138:139], off nt
	v_add_co_u32_e32 v138, vcc, s31, v140
	s_waitcnt vmcnt(1)
	v_lshlrev_b32_e32 v150, 16, v142
	v_addc_co_u32_e32 v139, vcc, 0, v141, vcc
	global_load_dwordx4 v[154:157], v[138:139], off nt
	v_lshl_add_u64 v[138:139], v[140:141], 0, s[42:43]
	s_mov_b64 s[42:43], 0x120000
	global_load_dwordx4 v[158:161], v[138:139], off offset:256 nt
	v_lshl_add_u64 v[138:139], v[140:141], 0, s[42:43]
	global_load_dwordx4 v[162:165], v[138:139], off offset:256 nt
	v_lshl_add_u64 v[138:139], v[140:141], 0, s[26:27]
	global_load_dwordx4 v[166:169], v[138:139], off offset:256 nt
	v_add_co_u32_e32 v138, vcc, s63, v140
	v_and_b32_e32 v151, 0xffff0000, v142
	s_nop 0
	v_addc_co_u32_e32 v139, vcc, 0, v141, vcc
	global_load_dwordx4 v[170:173], v[138:139], off nt
	v_lshl_add_u64 v[138:139], v[140:141], 0, s[28:29]
	global_load_dwordx4 v[138:141], v[138:139], off offset:256 nt
	v_lshlrev_b32_e32 v142, 16, v143
	v_and_b32_e32 v143, 0xffff0000, v143
	v_pk_mul_f32 v[54:55], v[54:55], v[142:143]
	s_waitcnt vmcnt(6)
	v_lshlrev_b32_e32 v142, 16, v149
	v_and_b32_e32 v143, 0xffff0000, v149
	v_pk_mul_f32 v[42:43], v[42:43], v[142:143]
	v_lshlrev_b32_e32 v174, 16, v144
	v_and_b32_e32 v175, 0xffff0000, v144
	v_lshlrev_b32_e32 v144, 16, v145
	v_and_b32_e32 v145, 0xffff0000, v145
	v_lshlrev_b32_e32 v176, 16, v146
	v_and_b32_e32 v177, 0xffff0000, v146
	v_lshlrev_b32_e32 v178, 16, v148
	v_and_b32_e32 v179, 0xffff0000, v148
	v_lshlrev_b32_e32 v146, 16, v147
	v_and_b32_e32 v147, 0xffff0000, v147
	v_pk_mul_f32 v[52:53], v[52:53], v[150:151]
	v_pk_mul_f32 v[48:49], v[48:49], v[174:175]
	v_pk_mul_f32 v[50:51], v[50:51], v[144:145]
	v_pk_mul_f32 v[44:45], v[44:45], v[176:177]
	v_pk_mul_f32 v[40:41], v[40:41], v[178:179]
	v_pk_mul_f32 v[46:47], v[46:47], v[146:147]
	s_waitcnt vmcnt(5)
	v_lshlrev_b32_e32 v180, 16, v154
	v_and_b32_e32 v181, 0xffff0000, v154
	v_lshlrev_b32_e32 v182, 16, v156
	v_and_b32_e32 v183, 0xffff0000, v156
	v_lshlrev_b32_e32 v154, 16, v155
	v_and_b32_e32 v155, 0xffff0000, v155
	v_lshlrev_b32_e32 v156, 16, v157
	s_waitcnt vmcnt(2)
	v_lshlrev_b32_e32 v142, 16, v166
	v_and_b32_e32 v143, 0xffff0000, v166
	v_pk_mul_f32 v[12:13], v[12:13], v[142:143]
	v_lshlrev_b32_e32 v142, 16, v168
	v_and_b32_e32 v143, 0xffff0000, v168
	v_pk_mul_f32 v[8:9], v[8:9], v[142:143]
	v_lshlrev_b32_e32 v142, 16, v167
	v_and_b32_e32 v143, 0xffff0000, v167
	v_pk_mul_f32 v[14:15], v[14:15], v[142:143]
	v_lshlrev_b32_e32 v142, 16, v169
	v_and_b32_e32 v143, 0xffff0000, v169
	v_pk_mul_f32 v[10:11], v[10:11], v[142:143]
	s_waitcnt vmcnt(1)
	v_lshlrev_b32_e32 v142, 16, v170
	v_and_b32_e32 v143, 0xffff0000, v170
	v_pk_mul_f32 v[36:37], v[36:37], v[142:143]
	v_lshlrev_b32_e32 v142, 16, v172
	v_and_b32_e32 v143, 0xffff0000, v172
	v_pk_mul_f32 v[32:33], v[32:33], v[142:143]
	v_lshlrev_b32_e32 v142, 16, v171
	v_and_b32_e32 v143, 0xffff0000, v171
	v_pk_mul_f32 v[38:39], v[38:39], v[142:143]
	v_lshlrev_b32_e32 v142, 16, v173
	v_and_b32_e32 v143, 0xffff0000, v173
	v_pk_mul_f32 v[34:35], v[34:35], v[142:143]
	s_waitcnt vmcnt(0)
	v_lshlrev_b32_e32 v142, 16, v138
	v_and_b32_e32 v143, 0xffff0000, v138
	v_lshlrev_b32_e32 v138, 16, v139
	v_and_b32_e32 v139, 0xffff0000, v139
	v_and_b32_e32 v157, 0xffff0000, v157
	v_lshlrev_b32_e32 v184, 16, v158
	v_and_b32_e32 v185, 0xffff0000, v158
	v_lshlrev_b32_e32 v186, 16, v160
	v_and_b32_e32 v187, 0xffff0000, v160
	v_lshlrev_b32_e32 v158, 16, v159
	v_and_b32_e32 v159, 0xffff0000, v159
	v_lshlrev_b32_e32 v160, 16, v161
	v_and_b32_e32 v161, 0xffff0000, v161
	v_lshlrev_b32_e32 v188, 16, v162
	v_and_b32_e32 v189, 0xffff0000, v162
	v_lshlrev_b32_e32 v190, 16, v164
	v_and_b32_e32 v191, 0xffff0000, v164
	v_lshlrev_b32_e32 v162, 16, v163
	v_and_b32_e32 v163, 0xffff0000, v163
	v_lshlrev_b32_e32 v164, 16, v165
	v_and_b32_e32 v165, 0xffff0000, v165
	v_pk_mul_f32 v[4:5], v[4:5], v[142:143]
	v_lshlrev_b32_e32 v142, 16, v140
	v_and_b32_e32 v143, 0xffff0000, v140
	v_pk_mul_f32 v[6:7], v[6:7], v[138:139]
	v_lshlrev_b32_e32 v138, 16, v141
	v_and_b32_e32 v139, 0xffff0000, v141
	v_pk_mul_f32 v[60:61], v[60:61], v[180:181]
	v_pk_mul_f32 v[56:57], v[56:57], v[182:183]
	v_pk_mul_f32 v[62:63], v[62:63], v[154:155]
	v_pk_mul_f32 v[58:59], v[58:59], v[156:157]
	v_pk_mul_f32 v[28:29], v[28:29], v[184:185]
	v_pk_mul_f32 v[24:25], v[24:25], v[186:187]
	v_pk_mul_f32 v[30:31], v[30:31], v[158:159]
	v_pk_mul_f32 v[26:27], v[26:27], v[160:161]
	v_pk_mul_f32 v[20:21], v[20:21], v[188:189]
	v_pk_mul_f32 v[16:17], v[16:17], v[190:191]
	v_pk_mul_f32 v[22:23], v[22:23], v[162:163]
	v_pk_mul_f32 v[18:19], v[18:19], v[164:165]
	v_pk_mul_f32 v[0:1], v[0:1], v[142:143]
	v_pk_mul_f32 v[2:3], v[2:3], v[138:139]
